# scanA/scanC: keep next-unit and unit-top loads in flight (no early drains), on top of scanC column-slice restructure
# baseline (speedup 1.0000x reference)
.LBB0_1203:
	s_or_b64 exec, exec, s[0:1]
	v_and_b32_e32 v25, 0xffff, v2
	v_lshrrev_b32_e32 v2, 16, v2
	v_lshl_or_b32 v25, v6, 16, v25
	v_and_or_b32 v2, v6, s28, v2
	v_add_u32_e32 v6, 0x5000, v59
	ds_write2_b32 v6, v25, v2 offset1:36
	v_and_b32_e32 v2, 0xffff, v3
	v_lshrrev_b32_e32 v3, 16, v3
	v_lshl_or_b32 v2, v7, 16, v2
	v_and_or_b32 v3, v7, s28, v3
	ds_write2_b32 v6, v2, v3 offset0:72 offset1:108
	v_and_b32_e32 v2, 0xffff, v4
	v_lshrrev_b32_e32 v3, 16, v4
	v_lshl_or_b32 v2, v8, 16, v2
	v_and_or_b32 v3, v8, s28, v3
	ds_write2_b32 v6, v2, v3 offset0:144 offset1:180
	v_and_b32_e32 v2, 0xffff, v5
	v_lshrrev_b32_e32 v3, 16, v5
	v_lshl_or_b32 v2, v9, 16, v2
	v_and_or_b32 v3, v9, s28, v3
	ds_write2_b32 v6, v2, v3 offset0:216 offset1:252
	s_waitcnt lgkmcnt(0)
	s_barrier
	ds_read_b128 v[2:5], v60 offset:2048
	ds_read_b128 v[6:9], v61 offset:20480
	ds_read_b128 v[30:33], v60 offset:2112
	ds_read_b128 v[34:37], v61 offset:20544
	ds_read_b128 v[38:41], v61 offset:22784
	ds_read_b128 v[42:45], v61 offset:22848
	ds_read_b128 v[46:49], v61 offset:25088
	ds_read_b128 v[78:81], v61 offset:25152
	ds_read_b128 v[82:85], v61 offset:27392
	ds_read_b128 v[86:89], v61 offset:27456
	ds_read_b128 v[90:93], v61 offset:29696
	ds_read_b128 v[94:97], v61 offset:29760
	ds_read_b128 v[98:101], v61 offset:32000
	ds_read_b128 v[102:105], v61 offset:32064
	ds_read_b128 v[106:109], v61 offset:34304
	ds_read_b128 v[110:113], v61 offset:34368
	ds_read_b128 v[114:117], v61 offset:36608
	ds_read_b128 v[118:121], v61 offset:36672
	s_waitcnt lgkmcnt(14)
	v_mfma_f32_16x16x32_bf16 v[6:9], v[2:5], v[6:9], 0
	s_lshl_b64 s[0:1], s[16:17], 18
	s_add_u32 s4, s90, s0
	s_addc_u32 s5, s91, s1
	s_waitcnt lgkmcnt(13)
	v_mfma_f32_16x16x32_bf16 v[38:41], v[2:5], v[38:41], 0
	s_ashr_i32 s15, s14, 31
	s_lshl_b64 s[0:1], s[14:15], 15
	s_add_u32 s0, s4, s0
	s_waitcnt lgkmcnt(11)
	v_mfma_f32_16x16x32_bf16 v[46:49], v[2:5], v[46:49], 0
	s_addc_u32 s1, s5, s1
	v_mov_b32_e32 v25, v19
	v_mov_b32_e32 v27, v19
	s_waitcnt lgkmcnt(9)
	v_mfma_f32_16x16x32_bf16 v[82:85], v[2:5], v[82:85], 0
	s_waitcnt lgkmcnt(7)
	v_mfma_f32_16x16x32_bf16 v[90:93], v[2:5], v[90:93], 0
	s_waitcnt lgkmcnt(5)
	v_mfma_f32_16x16x32_bf16 v[98:101], v[2:5], v[98:101], 0
	s_waitcnt lgkmcnt(3)
	v_mfma_f32_16x16x32_bf16 v[106:109], v[2:5], v[106:109], 0
	s_waitcnt lgkmcnt(1)
	v_mfma_f32_16x16x32_bf16 v[2:5], v[2:5], v[114:117], 0
	v_mfma_f32_16x16x32_bf16 v[6:9], v[30:33], v[34:37], v[6:9]
	v_mfma_f32_16x16x32_bf16 v[34:37], v[30:33], v[42:45], v[38:41]
	v_mfma_f32_16x16x32_bf16 v[38:41], v[30:33], v[78:81], v[46:49]
	s_nop 5
	v_cvt_pk_bf16_f32 v6, v6, v7
	v_cvt_pk_bf16_f32 v7, v8, v9
	v_mfma_f32_16x16x32_bf16 v[42:45], v[30:33], v[86:89], v[82:85]
	v_mfma_f32_16x16x32_bf16 v[46:49], v[30:33], v[94:97], v[90:93]
	v_mfma_f32_16x16x32_bf16 v[78:81], v[30:33], v[102:105], v[98:101]
	v_mfma_f32_16x16x32_bf16 v[82:85], v[30:33], v[110:113], v[106:109]
	s_waitcnt lgkmcnt(0)
	v_mfma_f32_16x16x32_bf16 v[2:5], v[30:33], v[118:121], v[2:5]
	v_lshl_add_u64 v[30:31], s[0:1], 0, v[18:19]
	v_lshl_add_u64 v[30:31], v[30:31], 0, v[24:25]
	v_lshl_add_u64 v[8:9], v[30:31], 0, v[26:27]
	v_add_co_u32_e32 v30, vcc, s20, v8
	global_store_dwordx2 v[8:9], v[6:7], off
	v_cvt_pk_bf16_f32 v6, v34, v35
	v_cvt_pk_bf16_f32 v7, v36, v37
	v_addc_co_u32_e32 v31, vcc, 0, v9, vcc
	global_store_dwordx2 v[30:31], v[6:7], off offset:-4096
	v_cvt_pk_bf16_f32 v6, v38, v39
	v_cvt_pk_bf16_f32 v7, v40, v41
	global_store_dwordx2 v[30:31], v[6:7], off
	v_add_co_u32_e32 v30, vcc, s29, v8
	v_cvt_pk_bf16_f32 v6, v42, v43
	v_cvt_pk_bf16_f32 v7, v44, v45
	v_addc_co_u32_e32 v31, vcc, 0, v9, vcc
	global_store_dwordx2 v[30:31], v[6:7], off offset:-4096
	v_cvt_pk_bf16_f32 v6, v46, v47
	v_cvt_pk_bf16_f32 v7, v48, v49
	global_store_dwordx2 v[30:31], v[6:7], off
	v_add_co_u32_e32 v30, vcc, s21, v8
	v_cvt_pk_bf16_f32 v6, v78, v79
	s_nop 0
	v_addc_co_u32_e32 v31, vcc, 0, v9, vcc
	v_cvt_pk_bf16_f32 v7, v80, v81
	v_cvt_pk_bf16_f32 v2, v2, v3
	v_cvt_pk_bf16_f32 v3, v4, v5
	v_add_co_u32_e32 v4, vcc, 0x7000, v8
	global_store_dwordx2 v[30:31], v[6:7], off offset:-4096
	v_cvt_pk_bf16_f32 v6, v82, v83
	v_cvt_pk_bf16_f32 v7, v84, v85
	v_addc_co_u32_e32 v5, vcc, 0, v9, vcc
	global_store_dwordx2 v[30:31], v[6:7], off
	global_store_dwordx2 v[4:5], v[2:3], off
	s_waitcnt vmcnt(8)
	v_lshlrev_b32_e32 v23, 16, v122
	v_lshlrev_b32_e32 v64, 16, v123
	v_lshlrev_b32_e32 v21, 16, v129
	v_lshlrev_b32_e32 v63, 16, v128
	v_lshlrev_b32_e32 v65, 16, v127
	v_lshlrev_b32_e32 v66, 16, v124
	v_lshlrev_b32_e32 v67, 16, v126
	v_lshlrev_b32_e32 v68, 16, v125
	v_lshlrev_b32_e32 v70, 16, v130
	v_lshlrev_b32_e32 v72, 16, v131
	v_lshlrev_b32_e32 v74, 16, v132
	v_lshlrev_b32_e32 v76, 16, v133
	v_lshlrev_b32_e32 v75, 16, v134
	v_lshlrev_b32_e32 v73, 16, v135
	v_lshlrev_b32_e32 v71, 16, v136
	v_lshlrev_b32_e32 v69, 16, v137
	v_mov_b32_e32 v77, v64
	v_mov_b64_e32 v[2:3], v[10:11]
	s_waitcnt vmcnt(8)
	v_mov_b64_e32 v[6:7], v[14:15]
	s_andn2_b64 vcc, exec, s[12:13]
	v_mov_b64_e32 v[4:5], v[12:13]
	v_mov_b64_e32 v[8:9], v[16:17]
	s_mov_b32 s0, s30
	v_mov_b32_e32 v27, v21
	v_mov_b32_e32 v25, v23
	v_mov_b32_e32 v78, v63
	v_mov_b32_e32 v80, v65
	v_mov_b32_e32 v79, v66
	v_mov_b32_e32 v82, v67
	v_mov_b32_e32 v81, v68
	v_mov_b32_e32 v44, v69
	v_mov_b32_e32 v83, v70
	v_mov_b32_e32 v38, v71
	v_mov_b32_e32 v45, v72
	v_mov_b32_e32 v34, v73
	v_mov_b32_e32 v39, v74
	v_mov_b32_e32 v84, v75
	v_mov_b32_e32 v35, v76
	s_barrier
	s_cbranch_vccz .LBB0_1210
.LBB0_1204:
	s_add_i32 s30, s0, s96
	s_cmpk_gt_i32 s30, 0x7ff
	s_cselect_b64 s[12:13], -1, 0
	s_and_b64 vcc, exec, s[12:13]
	s_cbranch_vccnz .LBB0_1206
	s_ashr_i32 s1, s30, 31
	s_lshr_b32 s1, s1, 29
	s_add_i32 s1, s30, s1
	s_and_b32 s4, s1, 0x1fffff8
	s_sub_i32 s4, s30, s4
	s_lshl_b32 s1, s1, 3
	s_lshl_b32 s4, s4, 7
	s_andn2_b32 s1, s1, 63
	v_add_u32_e32 v10, s4, v52
	v_or_b32_e32 v21, s1, v29
	v_mov_b32_e32 v11, v19
	v_lshl_add_u64 v[10:11], v[10:11], 1, s[10:11]
	v_or_b32_e32 v23, 3, v21
	v_mad_i64_i32 v[30:31], s[6:7], v23, s19, v[10:11]
	v_or_b32_e32 v23, 4, v21
	v_mad_i64_i32 v[32:33], s[6:7], v23, s19, v[10:11]
	v_or_b32_e32 v23, 5, v21
	v_mad_i64_i32 v[36:37], s[6:7], v23, s19, v[10:11]
	v_or_b32_e32 v23, 6, v21
	v_or_b32_e32 v14, 1, v21
	v_mad_i64_i32 v[40:41], s[6:7], v23, s19, v[10:11]
	v_or_b32_e32 v23, 7, v21
	v_mad_i64_i32 v[14:15], s[6:7], v14, s19, v[10:11]
	v_or_b32_e32 v16, 2, v21
	v_mad_i64_i32 v[42:43], s[6:7], v23, s19, v[10:11]
	v_or_b32_e32 v23, 11, v21
	v_mad_i64_i32 v[12:13], s[6:7], v21, s19, v[10:11]
	v_mad_i64_i32 v[16:17], s[6:7], v16, s19, v[10:11]
	global_load_ushort v122, v[14:15], off
	global_load_ushort v123, v[30:31], off
	global_load_ushort v124, v[36:37], off
	s_nop 0
	global_load_ushort v125, v[42:43], off
	s_nop 0
	global_load_ushort v126, v[40:41], off
	global_load_ushort v127, v[32:33], off
	global_load_ushort v128, v[16:17], off
	global_load_ushort v129, v[12:13], off
	v_mad_i64_i32 v[30:31], s[6:7], v23, s19, v[10:11]
	v_or_b32_e32 v23, 12, v21
	v_mad_i64_i32 v[32:33], s[6:7], v23, s19, v[10:11]
	v_or_b32_e32 v23, 13, v21
	v_or_b32_e32 v12, 8, v21
	v_or_b32_e32 v14, 9, v21
	v_or_b32_e32 v16, 10, v21
	v_mad_i64_i32 v[36:37], s[6:7], v23, s19, v[10:11]
	v_or_b32_e32 v23, 14, v21
	v_or_b32_e32 v21, 15, v21
	s_mul_hi_i32 s5, s1, 0x3a00
	s_mulk_i32 s1, 0x3a00
	v_mad_i64_i32 v[12:13], s[6:7], v12, s19, v[10:11]
	v_mad_i64_i32 v[14:15], s[6:7], v14, s19, v[10:11]
	v_mad_i64_i32 v[16:17], s[6:7], v16, s19, v[10:11]
	v_mad_i64_i32 v[40:41], s[6:7], v23, s19, v[10:11]
	v_mad_i64_i32 v[10:11], s[6:7], v21, s19, v[10:11]
	s_add_u32 s1, s10, s1
	s_addc_u32 s6, s11, s5
	s_ashr_i32 s5, s4, 31
	s_lshl_b64 s[4:5], s[4:5], 1
	s_add_u32 s4, s1, s4
	s_addc_u32 s5, s6, s5
	v_mov_b32_e32 v21, v19
	global_load_ushort v130, v[14:15], off
	s_nop 0
	global_load_ushort v131, v[30:31], off
	s_nop 0
	global_load_ushort v132, v[36:37], off
	s_nop 0
	global_load_ushort v133, v[10:11], off
	global_load_ushort v134, v[40:41], off
	s_nop 0
	global_load_ushort v135, v[32:33], off
	s_nop 0
	global_load_ushort v136, v[16:17], off
	global_load_ushort v137, v[12:13], off
	v_lshl_add_u64 v[10:11], s[4:5], 0, v[20:21]
	v_mov_b32_e32 v23, v19
	v_lshl_add_u64 v[10:11], v[10:11], 0, v[22:23]
	v_add_co_u32_e32 v12, vcc, 0x2000, v10
	v_addc_co_u32_e32 v13, vcc, 0, v11, vcc
	v_add_co_u32_e32 v14, vcc, 0x6000, v10
	v_addc_co_u32_e32 v15, vcc, 0, v11, vcc
	global_load_dwordx4 v[10:13], v[12:13], off offset:2048
	s_nop 0
	global_load_dwordx4 v[14:17], v[14:15], off offset:512

.LBB0_1339:
	s_mul_hi_i32 s0, s67, 0x2aaaaaab
	s_lshr_b32 s1, s0, 31
	s_ashr_i32 s0, s0, 1
	s_add_i32 s20, s0, s1
	s_mul_i32 s0, s20, -12
	s_add_i32 s36, s67, s0
	s_mov_b64 s[0:1], -1
	s_cmp_gt_i32 s36, 7
	s_mul_i32 s37, s20, 0xfffffa00
	s_mul_i32 s68, s20, 0xe8000
	s_cbranch_scc0 .LBB0_1367
	s_add_i32 s0, s46, s37
	s_mul_i32 s1, s20, 0xfffff400
	s_addk_i32 s0, 0xe800
	s_add_i32 s38, s49, s1
	s_mov_b32 s1, s25
	s_add_i32 s24, s38, 0xffffe800
	s_lshl_b32 s21, s20, 6
	s_lshl_b64 s[40:41], s[0:1], 1
	s_add_u32 s40, s26, s40
	s_addc_u32 s41, s27, s41
	v_or_b32_e32 v20, s21, v135
	v_mov_b64_e32 v[2:3], s[40:41]
	v_mad_i64_i32 v[4:5], s[40:41], v20, s53, v[2:3]
	v_mov_b32_e32 v151, v137
	v_lshl_add_u64 v[4:5], v[4:5], 0, v[150:151]
	v_or_b32_e32 v21, 1, v20
	v_add_co_u32_e32 v4, vcc, s48, v4
	v_mad_i64_i32 v[6:7], s[40:41], v21, s53, v[2:3]
	s_nop 0
	v_addc_co_u32_e32 v5, vcc, 0, v5, vcc
	v_lshl_add_u64 v[6:7], v[6:7], 0, v[150:151]
	v_or_b32_e32 v31, 2, v20
	v_add_co_u32_e32 v6, vcc, s48, v6
	v_mad_i64_i32 v[8:9], s[40:41], v31, s53, v[2:3]
	s_nop 0
	v_addc_co_u32_e32 v7, vcc, 0, v7, vcc
	v_lshl_add_u64 v[8:9], v[8:9], 0, v[150:151]
	v_or_b32_e32 v32, 3, v20
	v_add_co_u32_e32 v8, vcc, s48, v8
	v_mad_i64_i32 v[10:11], s[40:41], v32, s53, v[2:3]
	s_nop 0
	v_addc_co_u32_e32 v9, vcc, 0, v9, vcc
	v_lshl_add_u64 v[10:11], v[10:11], 0, v[150:151]
	v_or_b32_e32 v33, 4, v20
	v_add_co_u32_e32 v10, vcc, s48, v10
	v_mad_i64_i32 v[12:13], s[40:41], v33, s53, v[2:3]
	s_nop 0
	v_addc_co_u32_e32 v11, vcc, 0, v11, vcc
	v_lshl_add_u64 v[12:13], v[12:13], 0, v[150:151]
	v_or_b32_e32 v34, 5, v20
	v_add_co_u32_e32 v12, vcc, s48, v12
	v_mad_i64_i32 v[14:15], s[40:41], v34, s53, v[2:3]
	s_nop 0
	v_addc_co_u32_e32 v13, vcc, 0, v13, vcc
	v_lshl_add_u64 v[14:15], v[14:15], 0, v[150:151]
	v_or_b32_e32 v35, 6, v20
	v_add_co_u32_e32 v14, vcc, s48, v14
	v_mad_i64_i32 v[16:17], s[40:41], v35, s53, v[2:3]
	s_nop 0
	v_addc_co_u32_e32 v15, vcc, 0, v15, vcc
	v_lshl_add_u64 v[16:17], v[16:17], 0, v[150:151]
	v_or_b32_e32 v36, 7, v20
	v_add_co_u32_e32 v16, vcc, s48, v16
	v_mad_i64_i32 v[18:19], s[40:41], v36, s53, v[2:3]
	s_nop 0
	v_addc_co_u32_e32 v17, vcc, 0, v17, vcc
	v_lshl_add_u64 v[18:19], v[18:19], 0, v[150:151]
	v_add_co_u32_e32 v18, vcc, s48, v18
	v_or_b32_e32 v37, 8, v20
	s_nop 0
	v_addc_co_u32_e32 v19, vcc, 0, v19, vcc
	global_load_ushort v89, v[4:5], off offset:2048
	s_nop 0
	global_load_ushort v90, v[6:7], off offset:2048
	s_nop 0
	global_load_ushort v91, v[8:9], off offset:2048
	s_nop 0
	global_load_ushort v92, v[10:11], off offset:2048
	global_load_ushort v93, v[12:13], off offset:2048
	s_nop 0
	global_load_ushort v94, v[14:15], off offset:2048
	global_load_ushort v95, v[16:17], off offset:2048
	global_load_ushort v128, v[18:19], off offset:2048
	v_mad_i64_i32 v[4:5], s[40:41], v37, s53, v[2:3]
	v_lshl_add_u64 v[4:5], v[4:5], 0, v[150:151]
	v_add_co_u32_e32 v4, vcc, s48, v4
	v_or_b32_e32 v38, 9, v20
	s_nop 0
	v_addc_co_u32_e32 v5, vcc, 0, v5, vcc
	global_load_ushort v129, v[4:5], off offset:2048
	v_mad_i64_i32 v[4:5], s[40:41], v38, s53, v[2:3]
	v_lshl_add_u64 v[4:5], v[4:5], 0, v[150:151]
	v_or_b32_e32 v39, 10, v20
	v_add_co_u32_e32 v4, vcc, s48, v4
	v_or_b32_e32 v40, 11, v20
	s_nop 0
	v_addc_co_u32_e32 v5, vcc, 0, v5, vcc
	v_or_b32_e32 v41, 12, v20
	v_or_b32_e32 v42, 13, v20
	v_or_b32_e32 v44, 14, v20
	v_mad_i64_i32 v[14:15], s[40:41], v44, s53, v[2:3]
	v_lshl_add_u64 v[14:15], v[14:15], 0, v[150:151]
	v_or_b32_e32 v46, 15, v20
	s_mul_hi_i32 s1, s21, 0x3a00
	s_add_u32 s33, s26, s68
	s_mov_b32 s39, s25
	v_add_u32_e32 v136, s0, v134
	s_addc_u32 s1, s27, s1
	v_readlane_b32 s72, v255, 13
	v_readlane_b32 s73, v255, 14
	v_readlane_b32 s74, v255, 15
	v_readlane_b32 s75, v255, 16
	v_readlane_b32 s76, v255, 17
	v_readlane_b32 s77, v255, 18
	v_readlane_b32 s78, v255, 19
	v_readlane_b32 s79, v255, 20
	v_readlane_b32 s80, v255, 21
	v_readlane_b32 s81, v255, 22
	v_readlane_b32 s82, v255, 23
	v_readlane_b32 s83, v255, 24
	v_readlane_b32 s84, v255, 25
	v_readlane_b32 s85, v255, 26
	s_mov_b64 s[72:73], s[76:77]
	s_mov_b64 s[74:75], s[78:79]
	s_mov_b64 s[76:77], s[80:81]
	s_mov_b64 s[78:79], s[82:83]
	v_mov_b32_e32 v153, v137
	v_mov_b32_e32 v155, v137
	v_mov_b32_e32 v149, v137
	v_readfirstlane_b32 s69, v0
	v_mov_b32_e32 v157, v137
	v_readlane_b32 s86, v255, 27
	v_readlane_b32 s87, v255, 28
	s_mov_b64 s[80:81], s[84:85]
	v_mad_i64_i32 v[6:7], s[40:41], v39, s53, v[2:3]
	v_lshl_add_u64 v[6:7], v[6:7], 0, v[150:151]
	v_add_co_u32_e32 v6, vcc, s48, v6
	v_mad_i64_i32 v[8:9], s[40:41], v40, s53, v[2:3]
	s_nop 0
	v_addc_co_u32_e32 v7, vcc, 0, v7, vcc
	v_lshl_add_u64 v[8:9], v[8:9], 0, v[150:151]
	v_add_co_u32_e32 v8, vcc, s48, v8
	v_mad_i64_i32 v[10:11], s[40:41], v41, s53, v[2:3]
	s_nop 0
	v_addc_co_u32_e32 v9, vcc, 0, v9, vcc
	v_lshl_add_u64 v[10:11], v[10:11], 0, v[150:151]
	v_add_co_u32_e32 v10, vcc, s48, v10
	v_mad_i64_i32 v[12:13], s[40:41], v42, s53, v[2:3]
	s_nop 0
	v_addc_co_u32_e32 v11, vcc, 0, v11, vcc
	v_lshl_add_u64 v[12:13], v[12:13], 0, v[150:151]
	v_add_co_u32_e32 v12, vcc, s48, v12
	v_mad_i64_i32 v[2:3], s[40:41], v46, s53, v[2:3]
	s_nop 0
	v_addc_co_u32_e32 v13, vcc, 0, v13, vcc
	v_add_co_u32_e32 v14, vcc, s48, v14
	v_lshl_add_u64 v[2:3], v[2:3], 0, v[150:151]
	s_nop 0
	v_addc_co_u32_e32 v15, vcc, 0, v15, vcc
	v_add_co_u32_e32 v2, vcc, s48, v2
	s_lshl_b64 s[40:41], s[38:39], 1
	s_nop 0
	v_addc_co_u32_e32 v3, vcc, 0, v3, vcc
	global_load_ushort v43, v[4:5], off offset:2048
	global_load_ushort v45, v[6:7], off offset:2048
	global_load_ushort v47, v[8:9], off offset:2048
	global_load_ushort v48, v[10:11], off offset:2048
	global_load_ushort v52, v[12:13], off offset:2048
	global_load_ushort v54, v[14:15], off offset:2048
	global_load_ushort v59, v[2:3], off offset:2048
	v_lshl_add_u64 v[10:11], v[136:137], 1, s[92:93]
	s_add_u32 s40, s33, s40
	v_lshl_add_u64 v[72:73], v[10:11], 0, s[28:29]
	s_addc_u32 s41, s1, s41
	v_mad_i64_i32 v[10:11], s[0:1], v20, s53, v[72:73]
	v_mad_i64_i32 v[12:13], s[0:1], v21, s53, v[72:73]
	v_mad_i64_i32 v[14:15], s[0:1], v31, s53, v[72:73]
	v_mad_i64_i32 v[16:17], s[0:1], v32, s53, v[72:73]
	v_mad_i64_i32 v[18:19], s[0:1], v33, s53, v[72:73]
	v_mad_i64_i32 v[20:21], s[0:1], v34, s53, v[72:73]
	v_mad_i64_i32 v[32:33], s[0:1], v35, s53, v[72:73]
	v_mad_i64_i32 v[34:35], s[0:1], v36, s53, v[72:73]
	v_readfirstlane_b32 s0, v1
	s_lshl_b32 s0, s0, 4
	v_lshlrev_b64 v[2:3], 2, v[136:137]
	s_add_i32 s0, s0, s21
	v_lshl_add_u64 v[4:5], s[76:77], 0, v[2:3]
	s_ashr_i32 s1, s0, 31
	v_add_co_u32_e32 v6, vcc, s48, v4
	v_lshl_add_u64 v[2:3], s[78:79], 0, v[2:3]
	s_lshl_b64 s[0:1], s[0:1], 6
	v_addc_co_u32_e32 v7, vcc, 0, v5, vcc
	global_load_dword v51, v[4:5], off
	global_load_dword v50, v[4:5], off offset:2048
	global_load_dword v49, v[6:7], off offset:2048
	global_load_ushort v60, v[10:11], off
	global_load_ushort v64, v[12:13], off
	global_load_ushort v71, v[14:15], off
	global_load_ushort v74, v[16:17], off
	global_load_ushort v75, v[18:19], off
	global_load_ushort v76, v[20:21], off
	global_load_ushort v77, v[32:33], off
	global_load_ushort v78, v[34:35], off
	global_load_dword v53, v[2:3], off
	v_lshl_add_u64 v[2:3], v[144:145], 0, s[0:1]
	global_load_dwordx4 v[18:21], v[2:3], off
	v_add_co_u32_e32 v8, vcc, s54, v4
	s_bfe_u32 s71, s69, 0x20006
	s_nop 0
	v_addc_co_u32_e32 v9, vcc, 0, v5, vcc
	v_add_co_u32_e32 v6, vcc, s55, v4
	global_load_dword v70, v[8:9], off offset:-4096
	global_load_dword v68, v[8:9], off
	global_load_dword v65, v[8:9], off offset:2048
	v_addc_co_u32_e32 v7, vcc, 0, v5, vcc
	v_add_co_u32_e32 v2, vcc, s56, v4
	s_lshl_b32 s33, s71, 4
	s_nop 0
	v_addc_co_u32_e32 v3, vcc, 0, v5, vcc
	v_add_co_u32_e32 v8, vcc, s57, v4
	s_nop 0
	v_addc_co_u32_e32 v9, vcc, 0, v5, vcc
	v_add_co_u32_e32 v10, vcc, s58, v4
	s_nop 0
	v_addc_co_u32_e32 v11, vcc, 0, v5, vcc
	global_load_dword v66, v[6:7], off offset:2048
	global_load_dword v69, v[2:3], off offset:-4096
	global_load_dword v67, v[2:3], off
	global_load_dword v62, v[2:3], off offset:2048
	global_load_dword v61, v[10:11], off offset:-4096
	global_load_dword v58, v[10:11], off
	global_load_dword v56, v[10:11], off offset:2048
	v_add_co_u32_e32 v2, vcc, s59, v4
	v_mad_i64_i32 v[6:7], s[0:1], v39, s53, v[72:73]
	s_nop 0
	v_addc_co_u32_e32 v3, vcc, 0, v5, vcc
	global_load_dword v63, v[8:9], off offset:2048
	global_load_dword v57, v[2:3], off
	global_load_dword v55, v[2:3], off offset:2048
	v_mad_i64_i32 v[2:3], s[0:1], v37, s53, v[72:73]
	v_mad_i64_i32 v[4:5], s[0:1], v38, s53, v[72:73]
	global_load_ushort v38, v[2:3], off
	global_load_ushort v79, v[4:5], off
	global_load_ushort v80, v[6:7], off
	v_mad_i64_i32 v[2:3], s[0:1], v40, s53, v[72:73]
	v_mad_i64_i32 v[4:5], s[0:1], v41, s53, v[72:73]
	global_load_ushort v40, v[2:3], off
	global_load_ushort v81, v[4:5], off
	v_lshl_add_u64 v[2:3], s[40:41], 0, v[152:153]
	s_mov_b64 s[0:1], 0x3a00
	s_waitcnt vmcnt(37)
	v_lshlrev_b32_e32 v30, 16, v89
	v_lshlrev_b32_e32 v29, 16, v90
	v_lshlrev_b32_e32 v28, 16, v91
	v_lshlrev_b32_e32 v27, 16, v92
	v_lshlrev_b32_e32 v25, 16, v93
	v_lshlrev_b32_e32 v24, 16, v94
	v_lshlrev_b32_e32 v23, 16, v95
	v_lshlrev_b32_e32 v22, 16, v128
	v_lshlrev_b32_e32 v26, 16, v129
	v_mul_f32_e32 v30, 0x3db504f3, v30
	v_mul_f32_e32 v29, 0x3db504f3, v29
	v_lshlrev_b32_e32 v37, 16, v43
	s_waitcnt vmcnt(36)
	v_lshlrev_b32_e32 v36, 16, v45
	s_waitcnt vmcnt(35)
	v_lshlrev_b32_e32 v35, 16, v47
	v_lshl_add_u64 v[4:5], v[2:3], 0, s[0:1]
	s_waitcnt vmcnt(34)
	v_lshlrev_b32_e32 v34, 16, v48
	v_lshl_add_u64 v[6:7], v[2:3], 0, v[154:155]
	v_lshl_add_u64 v[8:9], v[4:5], 0, v[154:155]
	global_load_dwordx4 v[10:13], v[6:7], off
	global_load_dwordx4 v[14:17], v[8:9], off
	v_lshl_add_u64 v[2:3], v[2:3], 0, v[148:149]
	v_lshl_add_u64 v[6:7], v[4:5], 0, v[148:149]
	s_waitcnt vmcnt(35)
	v_lshlrev_b32_e32 v33, 16, v52
	s_waitcnt vmcnt(34)
	v_lshlrev_b32_e32 v32, 16, v54
	s_waitcnt vmcnt(33)
	v_lshlrev_b32_e32 v31, 16, v59
	global_load_dwordx4 v[2:5], v[2:3], off
	s_nop 0
	global_load_dwordx4 v[6:9], v[6:7], off
	v_or_b32_e32 v149, s33, v139
	v_mul_f32_e32 v28, 0x3db504f3, v28
	v_mul_f32_e32 v27, 0x3db504f3, v27
	v_mul_f32_e32 v25, 0x3db504f3, v25
	v_mul_f32_e32 v24, 0x3db504f3, v24
	v_mul_f32_e32 v23, 0x3db504f3, v23
	v_mul_f32_e32 v22, 0x3db504f3, v22
	v_mul_f32_e32 v26, 0x3db504f3, v26
	v_mul_f32_e32 v36, 0x3db504f3, v36
	v_mul_f32_e32 v35, 0x3db504f3, v35
	s_waitcnt vmcnt(31)
	v_lshlrev_b32_e32 v54, 16, v60
	s_waitcnt vmcnt(30)
	v_lshlrev_b32_e32 v52, 16, v64
	s_waitcnt vmcnt(29)
	v_lshlrev_b32_e32 v48, 16, v71
	s_waitcnt vmcnt(28)
	v_lshlrev_b32_e32 v47, 16, v74
	s_waitcnt vmcnt(27)
	v_lshlrev_b32_e32 v45, 16, v75
	s_waitcnt vmcnt(26)
	v_lshlrev_b32_e32 v43, 16, v76
	s_waitcnt vmcnt(25)
	v_lshlrev_b32_e32 v41, 16, v77
	v_mad_i64_i32 v[74:75], s[0:1], v42, s53, v[72:73]
	v_mad_i64_i32 v[76:77], s[0:1], v44, s53, v[72:73]
	v_mad_i64_i32 v[72:73], s[0:1], v46, s53, v[72:73]
	s_waitcnt vmcnt(22)
	v_readlane_b32 s0, v18, 0
	global_load_ushort v64, v[74:75], off
	global_load_ushort v59, v[76:77], off
	global_load_ushort v60, v[72:73], off
	v_fma_f32 v71, s0, v51, v53
	v_readlane_b32 s0, v19, 0
	v_lshlrev_b32_e32 v39, 16, v78
	v_mul_f32_e32 v34, 0x3db504f3, v34
	v_fmac_f32_e32 v71, s0, v50
	v_readlane_b32 s0, v20, 0
	v_mul_f32_e32 v33, 0x3db504f3, v33
	v_mul_f32_e32 v32, 0x3db504f3, v32
	s_waitcnt vmcnt(24)
	v_fmac_f32_e32 v71, s0, v70
	v_readlane_b32 s0, v21, 0
	v_mul_f32_e32 v31, 0x3db504f3, v31
	s_waitcnt vmcnt(11)
	v_lshlrev_b32_e32 v46, 16, v38
	v_fmac_f32_e32 v71, s0, v49
	v_readlane_b32 s0, v18, 1
	s_waitcnt vmcnt(10)
	v_lshlrev_b32_e32 v44, 16, v79
	s_waitcnt vmcnt(8)
	v_lshlrev_b32_e32 v40, 16, v40
	v_fmac_f32_e32 v71, s0, v68
	v_readlane_b32 s0, v19, 1
	s_waitcnt vmcnt(1)
	v_lshlrev_b32_e32 v59, 16, v59
	v_fmac_f32_e32 v71, s0, v65
	v_readlane_b32 s0, v20, 1
	s_waitcnt vmcnt(0)
	v_lshlrev_b32_e32 v60, 16, v60
	v_fmac_f32_e32 v71, s0, v69
	v_readlane_b32 s0, v21, 1
	s_nop 1
	v_fmac_f32_e32 v71, s0, v66
	v_readlane_b32 s0, v18, 2
	s_nop 1
	v_fmac_f32_e32 v71, s0, v67
	v_readlane_b32 s0, v19, 2
	s_nop 1
	v_fmac_f32_e32 v71, s0, v62
	v_readlane_b32 s0, v20, 2
	s_nop 1
	v_fmac_f32_e32 v71, s0, v61
	v_readlane_b32 s0, v21, 2
	s_nop 1
	v_fmac_f32_e32 v71, s0, v63
	v_readlane_b32 s0, v18, 3
	s_nop 1
	v_fmac_f32_e32 v71, s0, v58
	v_readlane_b32 s0, v19, 3
	s_nop 1
	v_fmac_f32_e32 v71, s0, v56
	v_readlane_b32 s0, v20, 3
	s_nop 1
	v_fmac_f32_e32 v71, s0, v57
	v_readlane_b32 s0, v21, 3
	s_nop 1
	v_fmac_f32_e32 v71, s0, v55
	v_readlane_b32 s0, v18, 4
	v_mul_f32_e64 v42, |v71|, s60
	v_exp_f32_e32 v72, v42
	v_fma_f32 v74, s0, v51, v53
	v_readlane_b32 s0, v19, 4
	v_min_f32_e32 v71, 0, v71
	v_add_f32_e32 v38, 1.0, v72
	v_fmac_f32_e32 v74, s0, v50
	v_readlane_b32 s0, v20, 4
	v_cmp_gt_f32_e32 vcc, s61, v38
	v_lshlrev_b32_e32 v42, 16, v80
	v_fmac_f32_e32 v74, s0, v70
	v_readlane_b32 s0, v21, 4
	v_cndmask_b32_e64 v72, 0, 32, vcc
	v_ldexp_f32 v38, v38, v72
	v_fmac_f32_e32 v74, s0, v49
	v_readlane_b32 s0, v18, 5
	v_log_f32_e32 v72, v38
	v_lshlrev_b32_e32 v38, 16, v81
	v_fmac_f32_e32 v74, s0, v68
	v_readlane_b32 s0, v19, 5
	v_mul_f32_e32 v73, 0x3f317217, v72
	v_fma_f32 v73, v72, s62, -v73
	v_fmac_f32_e32 v74, s0, v65
	v_readlane_b32 s0, v20, 5
	v_fmac_f32_e32 v73, 0x3377d1cf, v72
	v_fmac_f32_e32 v73, 0x3f317217, v72
	v_fmac_f32_e32 v74, s0, v69
	v_readlane_b32 s0, v21, 5
	s_nop 1
	v_fmac_f32_e32 v74, s0, v66
	v_readlane_b32 s0, v18, 6
	s_nop 1
	v_fmac_f32_e32 v74, s0, v67
	v_readlane_b32 s0, v19, 6
	s_nop 1
	v_fmac_f32_e32 v74, s0, v62
	v_readlane_b32 s0, v20, 6
	s_nop 1
	v_fmac_f32_e32 v74, s0, v61
	v_readlane_b32 s0, v21, 6
	s_nop 1
	v_fmac_f32_e32 v74, s0, v63
	v_readlane_b32 s0, v18, 7
	s_nop 1
	v_fmac_f32_e32 v74, s0, v58
	v_readlane_b32 s0, v19, 7
	s_nop 1
	v_fmac_f32_e32 v74, s0, v56
	v_readlane_b32 s0, v20, 7
	s_nop 1
	v_fmac_f32_e32 v74, s0, v57
	v_readlane_b32 s0, v21, 7
	s_nop 1
	v_fmac_f32_e32 v74, s0, v55
	v_mul_f32_e64 v75, |v74|, s60
	v_exp_f32_e32 v75, v75
	v_cmp_lt_f32_e64 s[0:1], |v72|, s63
	s_nop 1
	v_cndmask_b32_e64 v72, v72, v73, s[0:1]
	v_cndmask_b32_e32 v73, 0, v195, vcc
	v_sub_f32_e32 v72, v72, v73
	v_add_f32_e32 v73, 1.0, v75
	v_cmp_gt_f32_e32 vcc, s61, v73
	v_readlane_b32 s0, v18, 8
	v_sub_f32_e32 v71, v71, v72
	v_cndmask_b32_e64 v75, 0, 32, vcc
	v_ldexp_f32 v73, v73, v75
	v_fma_f32 v75, s0, v51, v53
	v_readlane_b32 s0, v19, 8
	v_log_f32_e32 v73, v73
	v_min_f32_e32 v72, 0, v74
	v_fmac_f32_e32 v75, s0, v50
	v_readlane_b32 s0, v20, 8
	v_mul_f32_e32 v74, 0x3f317217, v73
	v_fma_f32 v74, v73, s62, -v74
	v_fmac_f32_e32 v75, s0, v70
	v_readlane_b32 s0, v21, 8
	v_fmac_f32_e32 v74, 0x3377d1cf, v73
	v_fmac_f32_e32 v74, 0x3f317217, v73
	v_fmac_f32_e32 v75, s0, v49
	v_readlane_b32 s0, v18, 9
	v_fma_f32 v71, v71, s64, 0
	s_nop 0
	v_fmac_f32_e32 v75, s0, v68
	v_readlane_b32 s0, v19, 9
	s_nop 1
	v_fmac_f32_e32 v75, s0, v65
	v_readlane_b32 s0, v20, 9
	s_nop 1
	v_fmac_f32_e32 v75, s0, v69
	v_readlane_b32 s0, v21, 9
	s_nop 1
	v_fmac_f32_e32 v75, s0, v66
	v_readlane_b32 s0, v18, 10
	s_nop 1
	v_fmac_f32_e32 v75, s0, v67
	v_readlane_b32 s0, v19, 10
	s_nop 1
	v_fmac_f32_e32 v75, s0, v62
	v_readlane_b32 s0, v20, 10
	s_nop 1
	v_fmac_f32_e32 v75, s0, v61
	v_readlane_b32 s0, v21, 10
	s_nop 1
	v_fmac_f32_e32 v75, s0, v63
	v_readlane_b32 s0, v18, 11
	s_nop 1
	v_fmac_f32_e32 v75, s0, v58
	v_readlane_b32 s0, v19, 11
	s_nop 1
	v_fmac_f32_e32 v75, s0, v56
	v_readlane_b32 s0, v20, 11
	s_nop 1
	v_fmac_f32_e32 v75, s0, v57
	v_readlane_b32 s0, v21, 11
	s_nop 1
	v_fmac_f32_e32 v75, s0, v55
	v_mul_f32_e64 v76, |v75|, s60
	v_exp_f32_e32 v76, v76
	v_cmp_lt_f32_e64 s[0:1], |v73|, s63
	s_nop 1
	v_cndmask_b32_e64 v73, v73, v74, s[0:1]
	v_cndmask_b32_e32 v74, 0, v195, vcc
	v_sub_f32_e32 v73, v73, v74
	v_add_f32_e32 v74, 1.0, v76
	v_cmp_gt_f32_e32 vcc, s61, v74
	v_readlane_b32 s0, v18, 12
	v_sub_f32_e32 v72, v72, v73
	v_cndmask_b32_e64 v76, 0, 32, vcc
	v_ldexp_f32 v74, v74, v76
	v_fma_f32 v76, s0, v51, v53
	v_readlane_b32 s0, v19, 12
	v_log_f32_e32 v74, v74
	v_min_f32_e32 v73, 0, v75
	v_fmac_f32_e32 v76, s0, v50
	v_readlane_b32 s0, v20, 12
	v_mul_f32_e32 v75, 0x3f317217, v74
	v_fma_f32 v75, v74, s62, -v75
	v_fmac_f32_e32 v76, s0, v70
	v_readlane_b32 s0, v21, 12
	v_fmac_f32_e32 v75, 0x3377d1cf, v74
	v_fmac_f32_e32 v75, 0x3f317217, v74
	v_fmac_f32_e32 v76, s0, v49
	v_readlane_b32 s0, v18, 13
	v_fmamk_f32 v72, v72, 0x3d800000, v71
	s_nop 0
	v_fmac_f32_e32 v76, s0, v68
	v_readlane_b32 s0, v19, 13
	s_nop 1
	v_fmac_f32_e32 v76, s0, v65
	v_readlane_b32 s0, v20, 13
	s_nop 1
	v_fmac_f32_e32 v76, s0, v69
	v_readlane_b32 s0, v21, 13
	s_nop 1
	v_fmac_f32_e32 v76, s0, v66
	v_readlane_b32 s0, v18, 14
	s_nop 1
	v_fmac_f32_e32 v76, s0, v67
	v_readlane_b32 s0, v19, 14
	s_nop 1
	v_fmac_f32_e32 v76, s0, v62
	v_readlane_b32 s0, v20, 14
	s_nop 1
	v_fmac_f32_e32 v76, s0, v61
	v_readlane_b32 s0, v21, 14
	s_nop 1
	v_fmac_f32_e32 v76, s0, v63
	v_readlane_b32 s0, v18, 15
	s_nop 1
	v_fmac_f32_e32 v76, s0, v58
	v_readlane_b32 s0, v19, 15
	s_nop 1
	v_fmac_f32_e32 v76, s0, v56
	v_readlane_b32 s0, v20, 15
	s_nop 1
	v_fmac_f32_e32 v76, s0, v57
	v_readlane_b32 s0, v21, 15
	s_nop 1
	v_fmac_f32_e32 v76, s0, v55
	v_mul_f32_e64 v77, |v76|, s60
	v_exp_f32_e32 v77, v77
	v_cmp_lt_f32_e64 s[0:1], |v74|, s63
	s_nop 1
	v_cndmask_b32_e64 v74, v74, v75, s[0:1]
	v_cndmask_b32_e32 v75, 0, v195, vcc
	v_sub_f32_e32 v74, v74, v75
	v_add_f32_e32 v75, 1.0, v77
	v_cmp_gt_f32_e32 vcc, s61, v75
	v_readlane_b32 s0, v18, 16
	v_sub_f32_e32 v73, v73, v74
	v_cndmask_b32_e64 v77, 0, 32, vcc
	v_ldexp_f32 v75, v75, v77
	v_fma_f32 v77, s0, v51, v53
	v_readlane_b32 s0, v19, 16
	v_log_f32_e32 v75, v75
	v_min_f32_e32 v74, 0, v76
	v_fmac_f32_e32 v77, s0, v50
	v_readlane_b32 s0, v20, 16
	v_mul_f32_e32 v76, 0x3f317217, v75
	v_fma_f32 v76, v75, s62, -v76
	v_fmac_f32_e32 v77, s0, v70
	v_readlane_b32 s0, v21, 16
	v_fmac_f32_e32 v76, 0x3377d1cf, v75
	v_fmac_f32_e32 v76, 0x3f317217, v75
	v_fmac_f32_e32 v77, s0, v49
	v_readlane_b32 s0, v18, 17
	v_fmamk_f32 v73, v73, 0x3d800000, v72
	s_nop 0
	v_fmac_f32_e32 v77, s0, v68
	v_readlane_b32 s0, v19, 17
	s_nop 1
	v_fmac_f32_e32 v77, s0, v65
	v_readlane_b32 s0, v20, 17
	s_nop 1
	v_fmac_f32_e32 v77, s0, v69
	v_readlane_b32 s0, v21, 17
	s_nop 1
	v_fmac_f32_e32 v77, s0, v66
	v_readlane_b32 s0, v18, 18
	s_nop 1
	v_fmac_f32_e32 v77, s0, v67
	v_readlane_b32 s0, v19, 18
	s_nop 1
	v_fmac_f32_e32 v77, s0, v62
	v_readlane_b32 s0, v20, 18
	s_nop 1
	v_fmac_f32_e32 v77, s0, v61
	v_readlane_b32 s0, v21, 18
	s_nop 1
	v_fmac_f32_e32 v77, s0, v63
	v_readlane_b32 s0, v18, 19
	s_nop 1
	v_fmac_f32_e32 v77, s0, v58
	v_readlane_b32 s0, v19, 19
	s_nop 1
	v_fmac_f32_e32 v77, s0, v56
	v_readlane_b32 s0, v20, 19
	s_nop 1
	v_fmac_f32_e32 v77, s0, v57
	v_readlane_b32 s0, v21, 19
	s_nop 1
	v_fmac_f32_e32 v77, s0, v55
	v_mul_f32_e64 v78, |v77|, s60
	v_exp_f32_e32 v78, v78
	v_cmp_lt_f32_e64 s[0:1], |v75|, s63
	s_nop 1
	v_cndmask_b32_e64 v75, v75, v76, s[0:1]
	v_cndmask_b32_e32 v76, 0, v195, vcc
	v_sub_f32_e32 v75, v75, v76
	v_add_f32_e32 v76, 1.0, v78
	v_cmp_gt_f32_e32 vcc, s61, v76
	v_readlane_b32 s0, v18, 20
	v_sub_f32_e32 v74, v74, v75
	v_cndmask_b32_e64 v78, 0, 32, vcc
	v_ldexp_f32 v76, v76, v78
	v_fma_f32 v78, s0, v51, v53
	v_readlane_b32 s0, v19, 20
	v_log_f32_e32 v76, v76
	v_min_f32_e32 v75, 0, v77
	v_fmac_f32_e32 v78, s0, v50
	v_readlane_b32 s0, v20, 20
	v_mul_f32_e32 v77, 0x3f317217, v76
	v_fma_f32 v77, v76, s62, -v77
	v_fmac_f32_e32 v78, s0, v70
	v_readlane_b32 s0, v21, 20
	v_fmac_f32_e32 v77, 0x3377d1cf, v76
	v_fmac_f32_e32 v77, 0x3f317217, v76
	v_fmac_f32_e32 v78, s0, v49
	v_readlane_b32 s0, v18, 21
	v_fmamk_f32 v74, v74, 0x3d800000, v73
	s_nop 0
	v_fmac_f32_e32 v78, s0, v68
	v_readlane_b32 s0, v19, 21
	s_nop 1
	v_fmac_f32_e32 v78, s0, v65
	v_readlane_b32 s0, v20, 21
	s_nop 1
	v_fmac_f32_e32 v78, s0, v69
	v_readlane_b32 s0, v21, 21
	s_nop 1
	v_fmac_f32_e32 v78, s0, v66
	v_readlane_b32 s0, v18, 22
	s_nop 1
	v_fmac_f32_e32 v78, s0, v67
	v_readlane_b32 s0, v19, 22
	s_nop 1
	v_fmac_f32_e32 v78, s0, v62
	v_readlane_b32 s0, v20, 22
	s_nop 1
	v_fmac_f32_e32 v78, s0, v61
	v_readlane_b32 s0, v21, 22
	s_nop 1
	v_fmac_f32_e32 v78, s0, v63
	v_readlane_b32 s0, v18, 23
	s_nop 1
	v_fmac_f32_e32 v78, s0, v58
	v_readlane_b32 s0, v19, 23
	s_nop 1
	v_fmac_f32_e32 v78, s0, v56
	v_readlane_b32 s0, v20, 23
	s_nop 1
	v_fmac_f32_e32 v78, s0, v57
	v_readlane_b32 s0, v21, 23
	s_nop 1
	v_fmac_f32_e32 v78, s0, v55
	v_mul_f32_e64 v79, |v78|, s60
	v_exp_f32_e32 v79, v79
	v_cmp_lt_f32_e64 s[0:1], |v76|, s63
	s_nop 1
	v_cndmask_b32_e64 v76, v76, v77, s[0:1]
	v_cndmask_b32_e32 v77, 0, v195, vcc
	v_sub_f32_e32 v76, v76, v77
	v_add_f32_e32 v77, 1.0, v79
	v_cmp_gt_f32_e32 vcc, s61, v77
	v_readlane_b32 s0, v18, 24
	v_sub_f32_e32 v75, v75, v76
	v_cndmask_b32_e64 v79, 0, 32, vcc
	v_ldexp_f32 v77, v77, v79
	v_fma_f32 v79, s0, v51, v53
	v_readlane_b32 s0, v19, 24
	v_log_f32_e32 v77, v77
	v_min_f32_e32 v76, 0, v78
	v_fmac_f32_e32 v79, s0, v50
	v_readlane_b32 s0, v20, 24
	v_mul_f32_e32 v78, 0x3f317217, v77
	v_fma_f32 v78, v77, s62, -v78
	v_fmac_f32_e32 v79, s0, v70
	v_readlane_b32 s0, v21, 24
	v_fmac_f32_e32 v78, 0x3377d1cf, v77
	v_fmac_f32_e32 v78, 0x3f317217, v77
	v_fmac_f32_e32 v79, s0, v49
	v_readlane_b32 s0, v18, 25
	v_fmamk_f32 v75, v75, 0x3d800000, v74
	s_nop 0
	v_fmac_f32_e32 v79, s0, v68
	v_readlane_b32 s0, v19, 25
	s_nop 1
	v_fmac_f32_e32 v79, s0, v65
	v_readlane_b32 s0, v20, 25
	s_nop 1
	v_fmac_f32_e32 v79, s0, v69
	v_readlane_b32 s0, v21, 25
	s_nop 1
	v_fmac_f32_e32 v79, s0, v66
	v_readlane_b32 s0, v18, 26
	s_nop 1
	v_fmac_f32_e32 v79, s0, v67
	v_readlane_b32 s0, v19, 26
	s_nop 1
	v_fmac_f32_e32 v79, s0, v62
	v_readlane_b32 s0, v20, 26
	s_nop 1
	v_fmac_f32_e32 v79, s0, v61
	v_readlane_b32 s0, v21, 26
	s_nop 1
	v_fmac_f32_e32 v79, s0, v63
	v_readlane_b32 s0, v18, 27
	s_nop 1
	v_fmac_f32_e32 v79, s0, v58
	v_readlane_b32 s0, v19, 27
	s_nop 1
	v_fmac_f32_e32 v79, s0, v56
	v_readlane_b32 s0, v20, 27
	s_nop 1
	v_fmac_f32_e32 v79, s0, v57
	v_readlane_b32 s0, v21, 27
	s_nop 1
	v_fmac_f32_e32 v79, s0, v55
	v_mul_f32_e64 v80, |v79|, s60
	v_exp_f32_e32 v80, v80
	v_cmp_lt_f32_e64 s[0:1], |v77|, s63
	s_nop 1
	v_cndmask_b32_e64 v77, v77, v78, s[0:1]
	v_cndmask_b32_e32 v78, 0, v195, vcc
	v_sub_f32_e32 v77, v77, v78
	v_add_f32_e32 v78, 1.0, v80
	v_cmp_gt_f32_e32 vcc, s61, v78
	v_readlane_b32 s0, v18, 28
	v_sub_f32_e32 v76, v76, v77
	v_cndmask_b32_e64 v80, 0, 32, vcc
	v_ldexp_f32 v78, v78, v80
	v_fma_f32 v80, s0, v51, v53
	v_readlane_b32 s0, v19, 28
	v_log_f32_e32 v78, v78
	v_min_f32_e32 v77, 0, v79
	v_fmac_f32_e32 v80, s0, v50
	v_readlane_b32 s0, v20, 28
	v_mul_f32_e32 v79, 0x3f317217, v78
	v_fma_f32 v79, v78, s62, -v79
	v_fmac_f32_e32 v80, s0, v70
	v_readlane_b32 s0, v21, 28
	v_fmac_f32_e32 v79, 0x3377d1cf, v78
	v_fmac_f32_e32 v79, 0x3f317217, v78
	v_fmac_f32_e32 v80, s0, v49
	v_readlane_b32 s0, v18, 29
	v_fmamk_f32 v76, v76, 0x3d800000, v75
	s_nop 0
	v_fmac_f32_e32 v80, s0, v68
	v_readlane_b32 s0, v19, 29
	s_nop 1
	v_fmac_f32_e32 v80, s0, v65
	v_readlane_b32 s0, v20, 29
	s_nop 1
	v_fmac_f32_e32 v80, s0, v69
	v_readlane_b32 s0, v21, 29
	s_nop 1
	v_fmac_f32_e32 v80, s0, v66
	v_readlane_b32 s0, v18, 30
	s_nop 1
	v_fmac_f32_e32 v80, s0, v67
	v_readlane_b32 s0, v19, 30
	s_nop 1
	v_fmac_f32_e32 v80, s0, v62
	v_readlane_b32 s0, v20, 30
	s_nop 1
	v_fmac_f32_e32 v80, s0, v61
	v_readlane_b32 s0, v21, 30
	s_nop 1
	v_fmac_f32_e32 v80, s0, v63
	v_readlane_b32 s0, v18, 31
	s_nop 1
	v_fmac_f32_e32 v80, s0, v58
	v_readlane_b32 s0, v19, 31
	s_nop 1
	v_fmac_f32_e32 v80, s0, v56
	v_readlane_b32 s0, v20, 31
	s_nop 1
	v_fmac_f32_e32 v80, s0, v57
	v_readlane_b32 s0, v21, 31
	s_nop 1
	v_fmac_f32_e32 v80, s0, v55
	v_mul_f32_e64 v81, |v80|, s60
	v_exp_f32_e32 v81, v81
	v_cmp_lt_f32_e64 s[0:1], |v78|, s63
	s_nop 1
	v_cndmask_b32_e64 v78, v78, v79, s[0:1]
	v_cndmask_b32_e32 v79, 0, v195, vcc
	v_sub_f32_e32 v78, v78, v79
	v_add_f32_e32 v79, 1.0, v81
	v_cmp_gt_f32_e32 vcc, s61, v79
	v_readlane_b32 s0, v18, 32
	v_sub_f32_e32 v77, v77, v78
	v_cndmask_b32_e64 v81, 0, 32, vcc
	v_ldexp_f32 v79, v79, v81
	v_fma_f32 v81, s0, v51, v53
	v_readlane_b32 s0, v19, 32
	v_log_f32_e32 v79, v79
	v_min_f32_e32 v78, 0, v80
	v_fmac_f32_e32 v81, s0, v50
	v_readlane_b32 s0, v20, 32
	v_mul_f32_e32 v80, 0x3f317217, v79
	v_fma_f32 v80, v79, s62, -v80
	v_fmac_f32_e32 v81, s0, v70
	v_readlane_b32 s0, v21, 32
	v_fmac_f32_e32 v80, 0x3377d1cf, v79
	v_fmac_f32_e32 v80, 0x3f317217, v79
	v_fmac_f32_e32 v81, s0, v49
	v_readlane_b32 s0, v18, 33
	v_fmamk_f32 v77, v77, 0x3d800000, v76
	s_nop 0
	v_fmac_f32_e32 v81, s0, v68
	v_readlane_b32 s0, v19, 33
	s_nop 1
	v_fmac_f32_e32 v81, s0, v65
	v_readlane_b32 s0, v20, 33
	s_nop 1
	v_fmac_f32_e32 v81, s0, v69
	v_readlane_b32 s0, v21, 33
	s_nop 1
	v_fmac_f32_e32 v81, s0, v66
	v_readlane_b32 s0, v18, 34
	s_nop 1
	v_fmac_f32_e32 v81, s0, v67
	v_readlane_b32 s0, v19, 34
	s_nop 1
	v_fmac_f32_e32 v81, s0, v62
	v_readlane_b32 s0, v20, 34
	s_nop 1
	v_fmac_f32_e32 v81, s0, v61
	v_readlane_b32 s0, v21, 34
	s_nop 1
	v_fmac_f32_e32 v81, s0, v63
	v_readlane_b32 s0, v18, 35
	s_nop 1
	v_fmac_f32_e32 v81, s0, v58
	v_readlane_b32 s0, v19, 35
	s_nop 1
	v_fmac_f32_e32 v81, s0, v56
	v_readlane_b32 s0, v20, 35
	s_nop 1
	v_fmac_f32_e32 v81, s0, v57
	v_readlane_b32 s0, v21, 35
	s_nop 1
	v_fmac_f32_e32 v81, s0, v55
	v_mul_f32_e64 v82, |v81|, s60
	v_exp_f32_e32 v82, v82
	v_cmp_lt_f32_e64 s[0:1], |v79|, s63
	s_nop 1
	v_cndmask_b32_e64 v79, v79, v80, s[0:1]
	v_cndmask_b32_e32 v80, 0, v195, vcc
	v_sub_f32_e32 v79, v79, v80
	v_add_f32_e32 v80, 1.0, v82
	v_cmp_gt_f32_e32 vcc, s61, v80
	v_readlane_b32 s0, v18, 36
	v_sub_f32_e32 v78, v78, v79
	v_cndmask_b32_e64 v82, 0, 32, vcc
	v_ldexp_f32 v80, v80, v82
	v_fma_f32 v82, s0, v51, v53
	v_readlane_b32 s0, v19, 36
	v_log_f32_e32 v80, v80
	v_min_f32_e32 v79, 0, v81
	v_fmac_f32_e32 v82, s0, v50
	v_readlane_b32 s0, v20, 36
	v_mul_f32_e32 v81, 0x3f317217, v80
	v_fma_f32 v81, v80, s62, -v81
	v_fmac_f32_e32 v82, s0, v70
	v_readlane_b32 s0, v21, 36
	v_fmac_f32_e32 v81, 0x3377d1cf, v80
	v_fmac_f32_e32 v81, 0x3f317217, v80
	v_fmac_f32_e32 v82, s0, v49
	v_readlane_b32 s0, v18, 37
	v_fmamk_f32 v78, v78, 0x3d800000, v77
	s_nop 0
	v_fmac_f32_e32 v82, s0, v68
	v_readlane_b32 s0, v19, 37
	s_nop 1
	v_fmac_f32_e32 v82, s0, v65
	v_readlane_b32 s0, v20, 37
	s_nop 1
	v_fmac_f32_e32 v82, s0, v69
	v_readlane_b32 s0, v21, 37
	s_nop 1
	v_fmac_f32_e32 v82, s0, v66
	v_readlane_b32 s0, v18, 38
	s_nop 1
	v_fmac_f32_e32 v82, s0, v67
	v_readlane_b32 s0, v19, 38
	s_nop 1
	v_fmac_f32_e32 v82, s0, v62
	v_readlane_b32 s0, v20, 38
	s_nop 1
	v_fmac_f32_e32 v82, s0, v61
	v_readlane_b32 s0, v21, 38
	s_nop 1
	v_fmac_f32_e32 v82, s0, v63
	v_readlane_b32 s0, v18, 39
	s_nop 1
	v_fmac_f32_e32 v82, s0, v58
	v_readlane_b32 s0, v19, 39
	s_nop 1
	v_fmac_f32_e32 v82, s0, v56
	v_readlane_b32 s0, v20, 39
	s_nop 1
	v_fmac_f32_e32 v82, s0, v57
	v_readlane_b32 s0, v21, 39
	s_nop 1
	v_fmac_f32_e32 v82, s0, v55
	v_mul_f32_e64 v83, |v82|, s60
	v_exp_f32_e32 v83, v83
	v_cmp_lt_f32_e64 s[0:1], |v80|, s63
	s_nop 1
	v_cndmask_b32_e64 v80, v80, v81, s[0:1]
	v_cndmask_b32_e32 v81, 0, v195, vcc
	v_sub_f32_e32 v80, v80, v81
	v_add_f32_e32 v81, 1.0, v83
	v_cmp_gt_f32_e32 vcc, s61, v81
	v_readlane_b32 s0, v18, 40
	v_sub_f32_e32 v79, v79, v80
	v_cndmask_b32_e64 v83, 0, 32, vcc
	v_ldexp_f32 v81, v81, v83
	v_fma_f32 v83, s0, v51, v53
	v_readlane_b32 s0, v19, 40
	v_log_f32_e32 v81, v81
	v_min_f32_e32 v80, 0, v82
	v_fmac_f32_e32 v83, s0, v50
	v_readlane_b32 s0, v20, 40
	v_mul_f32_e32 v82, 0x3f317217, v81
	v_fma_f32 v82, v81, s62, -v82
	v_fmac_f32_e32 v83, s0, v70
	v_readlane_b32 s0, v21, 40
	v_fmac_f32_e32 v82, 0x3377d1cf, v81
	v_fmac_f32_e32 v82, 0x3f317217, v81
	v_fmac_f32_e32 v83, s0, v49
	v_readlane_b32 s0, v18, 41
	v_fmamk_f32 v79, v79, 0x3d800000, v78
	s_nop 0
	v_fmac_f32_e32 v83, s0, v68
	v_readlane_b32 s0, v19, 41
	s_nop 1
	v_fmac_f32_e32 v83, s0, v65
	v_readlane_b32 s0, v20, 41
	s_nop 1
	v_fmac_f32_e32 v83, s0, v69
	v_readlane_b32 s0, v21, 41
	s_nop 1
	v_fmac_f32_e32 v83, s0, v66
	v_readlane_b32 s0, v18, 42
	s_nop 1
	v_fmac_f32_e32 v83, s0, v67
	v_readlane_b32 s0, v19, 42
	s_nop 1
	v_fmac_f32_e32 v83, s0, v62
	v_readlane_b32 s0, v20, 42
	s_nop 1
	v_fmac_f32_e32 v83, s0, v61
	v_readlane_b32 s0, v21, 42
	s_nop 1
	v_fmac_f32_e32 v83, s0, v63
	v_readlane_b32 s0, v18, 43
	s_nop 1
	v_fmac_f32_e32 v83, s0, v58
	v_readlane_b32 s0, v19, 43
	s_nop 1
	v_fmac_f32_e32 v83, s0, v56
	v_readlane_b32 s0, v20, 43
	s_nop 1
	v_fmac_f32_e32 v83, s0, v57
	v_readlane_b32 s0, v21, 43
	s_nop 1
	v_fmac_f32_e32 v83, s0, v55
	v_mul_f32_e64 v84, |v83|, s60
	v_exp_f32_e32 v84, v84
	v_cmp_lt_f32_e64 s[0:1], |v81|, s63
	s_nop 1
	v_cndmask_b32_e64 v81, v81, v82, s[0:1]
	v_cndmask_b32_e32 v82, 0, v195, vcc
	v_sub_f32_e32 v81, v81, v82
	v_add_f32_e32 v82, 1.0, v84
	v_cmp_gt_f32_e32 vcc, s61, v82
	v_readlane_b32 s0, v18, 44
	v_sub_f32_e32 v80, v80, v81
	v_cndmask_b32_e64 v84, 0, 32, vcc
	v_ldexp_f32 v82, v82, v84
	v_fma_f32 v84, s0, v51, v53
	v_readlane_b32 s0, v19, 44
	v_log_f32_e32 v82, v82
	v_min_f32_e32 v81, 0, v83
	v_fmac_f32_e32 v84, s0, v50
	v_readlane_b32 s0, v20, 44
	v_mul_f32_e32 v83, 0x3f317217, v82
	v_fma_f32 v83, v82, s62, -v83
	v_fmac_f32_e32 v84, s0, v70
	v_readlane_b32 s0, v21, 44
	v_fmac_f32_e32 v83, 0x3377d1cf, v82
	v_fmac_f32_e32 v83, 0x3f317217, v82
	v_fmac_f32_e32 v84, s0, v49
	v_readlane_b32 s0, v18, 45
	v_fmamk_f32 v80, v80, 0x3d800000, v79
	s_nop 0
	v_fmac_f32_e32 v84, s0, v68
	v_readlane_b32 s0, v19, 45
	s_nop 1
	v_fmac_f32_e32 v84, s0, v65
	v_readlane_b32 s0, v20, 45
	s_nop 1
	v_fmac_f32_e32 v84, s0, v69
	v_readlane_b32 s0, v21, 45
	s_nop 1
	v_fmac_f32_e32 v84, s0, v66
	v_readlane_b32 s0, v18, 46
	s_nop 1
	v_fmac_f32_e32 v84, s0, v67
	v_readlane_b32 s0, v19, 46
	s_nop 1
	v_fmac_f32_e32 v84, s0, v62
	v_readlane_b32 s0, v20, 46
	s_nop 1
	v_fmac_f32_e32 v84, s0, v61
	v_readlane_b32 s0, v21, 46
	s_nop 1
	v_fmac_f32_e32 v84, s0, v63
	v_readlane_b32 s0, v18, 47
	s_nop 1
	v_fmac_f32_e32 v84, s0, v58
	v_readlane_b32 s0, v19, 47
	s_nop 1
	v_fmac_f32_e32 v84, s0, v56
	v_readlane_b32 s0, v20, 47
	s_nop 1
	v_fmac_f32_e32 v84, s0, v57
	v_readlane_b32 s0, v21, 47
	s_nop 1
	v_fmac_f32_e32 v84, s0, v55
	v_mul_f32_e64 v85, |v84|, s60
	v_exp_f32_e32 v85, v85
	v_cmp_lt_f32_e64 s[0:1], |v82|, s63
	s_nop 1
	v_cndmask_b32_e64 v82, v82, v83, s[0:1]
	v_cndmask_b32_e32 v83, 0, v195, vcc
	v_sub_f32_e32 v82, v82, v83
	v_add_f32_e32 v83, 1.0, v85
	v_cmp_gt_f32_e32 vcc, s61, v83
	v_readlane_b32 s0, v18, 48
	v_sub_f32_e32 v81, v81, v82
	v_cndmask_b32_e64 v85, 0, 32, vcc
	v_ldexp_f32 v83, v83, v85
	v_fma_f32 v85, s0, v51, v53
	v_readlane_b32 s0, v19, 48
	v_log_f32_e32 v83, v83
	v_min_f32_e32 v82, 0, v84
	v_fmac_f32_e32 v85, s0, v50
	v_readlane_b32 s0, v20, 48
	v_mul_f32_e32 v84, 0x3f317217, v83
	v_fma_f32 v84, v83, s62, -v84
	v_fmac_f32_e32 v85, s0, v70
	v_readlane_b32 s0, v21, 48
	v_fmac_f32_e32 v84, 0x3377d1cf, v83
	v_fmac_f32_e32 v84, 0x3f317217, v83
	v_fmac_f32_e32 v85, s0, v49
	v_readlane_b32 s0, v18, 49
	v_fmamk_f32 v81, v81, 0x3d800000, v80
	s_nop 0
	v_fmac_f32_e32 v85, s0, v68
	v_readlane_b32 s0, v19, 49
	s_nop 1
	v_fmac_f32_e32 v85, s0, v65
	v_readlane_b32 s0, v20, 49
	s_nop 1
	v_fmac_f32_e32 v85, s0, v69
	v_readlane_b32 s0, v21, 49
	s_nop 1
	v_fmac_f32_e32 v85, s0, v66
	v_readlane_b32 s0, v18, 50
	s_nop 1
	v_fmac_f32_e32 v85, s0, v67
	v_readlane_b32 s0, v19, 50
	s_nop 1
	v_fmac_f32_e32 v85, s0, v62
	v_readlane_b32 s0, v20, 50
	s_nop 1
	v_fmac_f32_e32 v85, s0, v61
	v_readlane_b32 s0, v21, 50
	s_nop 1
	v_fmac_f32_e32 v85, s0, v63
	v_readlane_b32 s0, v18, 51
	s_nop 1
	v_fmac_f32_e32 v85, s0, v58
	v_readlane_b32 s0, v19, 51
	s_nop 1
	v_fmac_f32_e32 v85, s0, v56
	v_readlane_b32 s0, v20, 51
	s_nop 1
	v_fmac_f32_e32 v85, s0, v57
	v_readlane_b32 s0, v21, 51
	s_nop 1
	v_fmac_f32_e32 v85, s0, v55
	v_mul_f32_e64 v86, |v85|, s60
	v_exp_f32_e32 v86, v86
	v_cmp_lt_f32_e64 s[0:1], |v83|, s63
	s_nop 1
	v_cndmask_b32_e64 v83, v83, v84, s[0:1]
	v_cndmask_b32_e32 v84, 0, v195, vcc
	v_sub_f32_e32 v83, v83, v84
	v_add_f32_e32 v84, 1.0, v86
	v_cmp_gt_f32_e32 vcc, s61, v84
	v_readlane_b32 s0, v18, 52
	v_sub_f32_e32 v82, v82, v83
	v_cndmask_b32_e64 v86, 0, 32, vcc
	v_ldexp_f32 v84, v84, v86
	v_fma_f32 v86, s0, v51, v53
	v_readlane_b32 s0, v19, 52
	v_log_f32_e32 v84, v84
	v_min_f32_e32 v83, 0, v85
	v_fmac_f32_e32 v86, s0, v50
	v_readlane_b32 s0, v20, 52
	v_mul_f32_e32 v85, 0x3f317217, v84
	v_fma_f32 v85, v84, s62, -v85
	v_fmac_f32_e32 v86, s0, v70
	v_readlane_b32 s0, v21, 52
	v_fmac_f32_e32 v85, 0x3377d1cf, v84
	v_fmac_f32_e32 v85, 0x3f317217, v84
	v_fmac_f32_e32 v86, s0, v49
	v_readlane_b32 s0, v18, 53
	v_fmamk_f32 v82, v82, 0x3d800000, v81
	s_nop 0
	v_fmac_f32_e32 v86, s0, v68
	v_readlane_b32 s0, v19, 53
	s_nop 1
	v_fmac_f32_e32 v86, s0, v65
	v_readlane_b32 s0, v20, 53
	s_nop 1
	v_fmac_f32_e32 v86, s0, v69
	v_readlane_b32 s0, v21, 53
	s_nop 1
	v_fmac_f32_e32 v86, s0, v66
	v_readlane_b32 s0, v18, 54
	s_nop 1
	v_fmac_f32_e32 v86, s0, v67
	v_readlane_b32 s0, v19, 54
	s_nop 1
	v_fmac_f32_e32 v86, s0, v62
	v_readlane_b32 s0, v20, 54
	s_nop 1
	v_fmac_f32_e32 v86, s0, v61
	v_readlane_b32 s0, v21, 54
	s_nop 1
	v_fmac_f32_e32 v86, s0, v63
	v_readlane_b32 s0, v18, 55
	s_nop 1
	v_fmac_f32_e32 v86, s0, v58
	v_readlane_b32 s0, v19, 55
	s_nop 1
	v_fmac_f32_e32 v86, s0, v56
	v_readlane_b32 s0, v20, 55
	s_nop 1
	v_fmac_f32_e32 v86, s0, v57
	v_readlane_b32 s0, v21, 55
	s_nop 1
	v_fmac_f32_e32 v86, s0, v55
	v_mul_f32_e64 v87, |v86|, s60
	v_exp_f32_e32 v87, v87
	v_cmp_lt_f32_e64 s[0:1], |v84|, s63
	s_nop 1
	v_cndmask_b32_e64 v84, v84, v85, s[0:1]
	v_cndmask_b32_e32 v85, 0, v195, vcc
	v_sub_f32_e32 v84, v84, v85
	v_add_f32_e32 v85, 1.0, v87
	v_cmp_gt_f32_e32 vcc, s61, v85
	v_readlane_b32 s0, v18, 56
	v_sub_f32_e32 v83, v83, v84
	v_cndmask_b32_e64 v87, 0, 32, vcc
	v_ldexp_f32 v85, v85, v87
	v_fma_f32 v87, s0, v51, v53
	v_readlane_b32 s0, v19, 56
	v_log_f32_e32 v85, v85
	v_min_f32_e32 v84, 0, v86
	v_fmac_f32_e32 v87, s0, v50
	v_readlane_b32 s0, v20, 56
	v_mul_f32_e32 v86, 0x3f317217, v85
	v_fma_f32 v86, v85, s62, -v86
	v_fmac_f32_e32 v87, s0, v70
	v_readlane_b32 s0, v21, 56
	v_fmac_f32_e32 v86, 0x3377d1cf, v85
	v_fmac_f32_e32 v86, 0x3f317217, v85
	v_fmac_f32_e32 v87, s0, v49
	v_readlane_b32 s0, v18, 57
	v_fmamk_f32 v83, v83, 0x3d800000, v82
	s_nop 0
	v_fmac_f32_e32 v87, s0, v68
	v_readlane_b32 s0, v19, 57
	s_nop 1
	v_fmac_f32_e32 v87, s0, v65
	v_readlane_b32 s0, v20, 57
	s_nop 1
	v_fmac_f32_e32 v87, s0, v69
	v_readlane_b32 s0, v21, 57
	s_nop 1
	v_fmac_f32_e32 v87, s0, v66
	v_readlane_b32 s0, v18, 58
	s_nop 1
	v_fmac_f32_e32 v87, s0, v67
	v_readlane_b32 s0, v19, 58
	s_nop 1
	v_fmac_f32_e32 v87, s0, v62
	v_readlane_b32 s0, v20, 58
	s_nop 1
	v_fmac_f32_e32 v87, s0, v61
	v_readlane_b32 s0, v21, 58
	s_nop 1
	v_fmac_f32_e32 v87, s0, v63
	v_readlane_b32 s0, v18, 59
	s_nop 1
	v_fmac_f32_e32 v87, s0, v58
	v_readlane_b32 s0, v19, 59
	s_nop 1
	v_fmac_f32_e32 v87, s0, v56
	v_readlane_b32 s0, v20, 59
	s_nop 1
	v_fmac_f32_e32 v87, s0, v57
	v_readlane_b32 s0, v21, 59
	s_nop 1
	v_fmac_f32_e32 v87, s0, v55
	v_cmp_lt_f32_e64 s[0:1], |v85|, s63
	v_mul_f32_e64 v88, |v87|, s60
	v_exp_f32_e32 v88, v88
	v_cndmask_b32_e64 v85, v85, v86, s[0:1]
	v_readlane_b32 s0, v18, 60
	v_cndmask_b32_e32 v86, 0, v195, vcc
	v_sub_f32_e32 v85, v85, v86
	v_fmac_f32_e32 v53, s0, v51
	v_readlane_b32 s0, v19, 60
	v_add_f32_e32 v86, 1.0, v88
	v_cmp_gt_f32_e32 vcc, s61, v86
	v_fmac_f32_e32 v53, s0, v50
	v_readlane_b32 s0, v20, 60
	v_cndmask_b32_e64 v88, 0, 32, vcc
	v_ldexp_f32 v86, v86, v88
	v_fmac_f32_e32 v53, s0, v70
	v_readlane_b32 s0, v21, 60
	v_log_f32_e32 v86, v86
	v_sub_f32_e32 v84, v84, v85
	v_fmac_f32_e32 v53, s0, v49
	v_readlane_b32 s0, v18, 61
	v_min_f32_e32 v85, 0, v87
	v_mul_f32_e32 v87, 0x3f317217, v86
	v_fmac_f32_e32 v53, s0, v68
	v_readlane_b32 s0, v19, 61
	v_fma_f32 v87, v86, s62, -v87
	v_fmac_f32_e32 v87, 0x3377d1cf, v86
	v_fmac_f32_e32 v53, s0, v65
	v_readlane_b32 s0, v20, 61
	v_fmac_f32_e32 v87, 0x3f317217, v86
	v_fmamk_f32 v84, v84, 0x3d800000, v83
	v_fmac_f32_e32 v53, s0, v69
	v_readlane_b32 s0, v21, 61
	s_nop 1
	v_fmac_f32_e32 v53, s0, v66
	v_readlane_b32 s0, v18, 62
	s_nop 1
	v_fmac_f32_e32 v53, s0, v67
	v_readlane_b32 s0, v19, 62
	s_nop 1
	v_fmac_f32_e32 v53, s0, v62
	v_readlane_b32 s0, v20, 62
	s_nop 1
	v_fmac_f32_e32 v53, s0, v61
	v_readlane_b32 s0, v21, 62
	s_nop 1
	v_fmac_f32_e32 v53, s0, v63
	v_readlane_b32 s0, v18, 63
	s_nop 1
	v_fmac_f32_e32 v53, s0, v58
	v_readlane_b32 s0, v19, 63
	v_lshlrev_b32_e32 v58, 16, v64
	s_nop 0
	v_fmac_f32_e32 v53, s0, v56
	v_readlane_b32 s0, v20, 63
	v_cndmask_b32_e32 v20, 0, v195, vcc
	s_nop 0
	v_fmac_f32_e32 v53, s0, v57
	v_readlane_b32 s0, v21, 63
	s_nop 1
	v_fmac_f32_e32 v53, s0, v55
	v_mul_f32_e64 v18, |v53|, s60
	v_exp_f32_e32 v18, v18
	v_cmp_lt_f32_e64 s[0:1], |v86|, s63
	v_add_f32_e32 v18, 1.0, v18
	s_nop 0
	v_cndmask_b32_e64 v19, v86, v87, s[0:1]
	v_cmp_gt_f32_e32 vcc, s61, v18
	v_sub_f32_e32 v19, v19, v20
	v_sub_f32_e32 v19, v85, v19
	v_cndmask_b32_e64 v20, 0, 32, vcc
	v_ldexp_f32 v18, v18, v20
	v_log_f32_e32 v18, v18
	v_fmamk_f32 v55, v19, 0x3d800000, v84
	v_min_f32_e32 v19, 0, v53
	v_mul_f32_e32 v20, 0x3f317217, v18
	v_fma_f32 v20, v18, s62, -v20
	v_fmac_f32_e32 v20, 0x3377d1cf, v18
	v_fmac_f32_e32 v20, 0x3f317217, v18
	v_cmp_lt_f32_e64 s[0:1], |v18|, s63
	s_nop 1
	v_cndmask_b32_e64 v18, v18, v20, s[0:1]
	v_cndmask_b32_e32 v20, 0, v195, vcc
	v_sub_f32_e32 v18, v18, v20
	v_sub_f32_e32 v18, v19, v18
	v_fmamk_f32 v53, v18, 0x3d800000, v55
	ds_write_b32 v141, v53
	s_waitcnt lgkmcnt(0)
	s_barrier
	ds_read2st64_b32 v[18:19], v143 offset1:2
	ds_read2st64_b32 v[50:51], v143 offset0:4 offset1:6
	v_or_b32_e32 v20, s21, v149
	s_waitcnt lgkmcnt(1)
	v_add_f32_e32 v49, 0, v18
	v_add_f32_e32 v21, v49, v19
	s_waitcnt lgkmcnt(0)
	v_add_f32_e32 v18, v21, v50
	v_add_f32_e32 v19, v18, v51
	v_mov_b64_e32 v[50:51], s[26:27]
	v_mad_i64_i32 v[174:175], s[0:1], v20, s53, v[50:51]
	s_lshr_b32 s0, s69, 1
	v_lshl_add_u64 v[50:51], s[24:25], 1, v[174:175]
	s_and_b32 s70, s0, 0x7fffff80
	v_lshl_add_u64 v[50:51], v[50:51], 0, v[156:157]
	s_lshl_b32 s0, s70, 1
	s_mov_b32 s1, s25
	v_lshl_add_u64 v[50:51], v[50:51], 0, s[0:1]
	v_lshl_add_u64 v[56:57], v[50:51], 0, s[30:31]
	v_add_co_u32_e32 v50, vcc, s54, v50
	s_nop 1
	v_addc_co_u32_e32 v51, vcc, 0, v51, vcc
	v_cmp_eq_u32_e32 vcc, 1, v1
	s_mul_hi_u32 s99, s67, 0xaaaaaaab
	v_and_b32_e32 v86, 15, v0
	v_bfe_u32 v87, v0, 4, 2
	v_lshrrev_b32_e32 v88, 6, v0
	s_lshr_b32 s99, s99, 3
	s_mul_i32 s100, s99, 12
	s_sub_u32 s100, s67, s100
	s_lshl_b32 s101, s99, 2
	s_add_i32 s101, s101, s100
	s_add_i32 s101, s101, -8
	s_lshl_b32 s101, s101, 16
	s_add_u32 s0, s44, s101
	s_addc_u32 s1, s45, 0
	v_lshlrev_b32_e32 v89, 8, v86
	v_lshl_add_u32 v89, v87, 4, v89
	v_lshl_add_u32 v89, v88, 13, v89
	global_load_dwordx4 v[208:211], v89, s[0:1]
	global_load_dwordx4 v[212:215], v89, s[0:1] offset:64
	global_load_dwordx4 v[216:219], v89, s[0:1] offset:128
	global_load_dwordx4 v[220:223], v89, s[0:1] offset:192
	v_add_u32_e32 v90, 0x1000, v89
	global_load_dwordx4 v[224:227], v90, s[0:1]
	global_load_dwordx4 v[228:231], v90, s[0:1] offset:64
	global_load_dwordx4 v[232:235], v90, s[0:1] offset:128
	global_load_dwordx4 v[236:239], v90, s[0:1] offset:192
	s_mul_i32 s99, s99, 0xe8000
	s_lshl_b32 s101, s100, 9
	s_add_i32 s99, s99, s101
	s_addk_i32 s99, 6144
	v_mul_u32_u24_e32 v92, 0x3a00, v86
	v_lshl_add_u32 v92, v87, 3, v92
	v_lshl_add_u32 v92, v88, 6, v92
	v_add_u32_e32 v92, s99, v92
	v_mov_b32_e32 v93, 0
	s_mov_b64 s[98:99], 0x3a000
	v_lshl_add_u64 v[120:121], v[92:93], 0, s[26:27]
	v_lshl_add_u64 v[122:123], v[120:121], 0, s[98:99]
	v_lshl_add_u64 v[124:125], v[122:123], 0, s[98:99]
	v_lshl_add_u64 v[126:127], v[124:125], 0, s[98:99]
	global_load_dwordx2 v[96:97], v[120:121], off offset:-2048
	global_load_dwordx2 v[98:99], v[120:121], off offset:-2016
	global_load_dwordx2 v[100:101], v[122:123], off offset:-2048
	global_load_dwordx2 v[102:103], v[122:123], off offset:-2016
	global_load_dwordx2 v[104:105], v[124:125], off offset:-2048
	global_load_dwordx2 v[106:107], v[124:125], off offset:-2016
	global_load_dwordx2 v[108:109], v[126:127], off offset:-2048
	global_load_dwordx2 v[110:111], v[126:127], off offset:-2016
	v_readlane_b32 s98, v255, 25
	v_readlane_b32 s99, v255, 26
	s_lshl_b32 s101, s100, 10
	s_addk_i32 s101, 0xe000
	v_lshl_add_u32 v94, v87, 4, s101
	v_lshl_add_u32 v94, v88, 7, v94
	s_nop 3
	global_load_dwordx4 v[112:115], v94, s[98:99]
	global_load_dwordx4 v[116:119], v94, s[98:99] offset:64
	v_cndmask_b32_e32 v20, 0, v49, vcc
	v_cmp_eq_u32_e32 vcc, 2, v1
	v_mul_f32_e32 v51, 0x3fb8aa3b, v72
	v_exp_f32_e32 v51, v51
	v_cndmask_b32_e32 v20, v20, v21, vcc
	v_cmp_eq_u32_e32 vcc, 3, v1
	v_mul_f32_e32 v29, v29, v51
	s_nop 0
	v_cndmask_b32_e32 v20, v20, v18, vcc
	v_cmp_eq_u32_e32 vcc, 4, v1
	v_mul_f32_e32 v51, 0x3fb8aa3b, v73
	v_exp_f32_e32 v51, v51
	v_cndmask_b32_e32 v19, v20, v19, vcc
	v_mul_f32_e32 v20, 0x3fb8aa3b, v71
	v_exp_f32_e32 v20, v20
	v_mul_f32_e32 v50, 0x3fb8aa3b, v19
	v_exp_f32_e32 v50, v50
	v_mul_f32_e32 v28, v28, v51
	v_mul_f32_e32 v20, v30, v20
	v_cvt_pk_bf16_f32 v30, v20, s0
	ds_write_b16 v191, v30 offset:2560
	v_mul_f32_e32 v30, 0xbfb8aa3b, v71
	v_exp_f32_e32 v30, v30
	v_mul_f32_e32 v20, v20, v50
	v_cvt_pk_bf16_f32 v20, v20, s0
	ds_write_b16 v191, v20 offset:19968
	v_mul_f32_e32 v20, v30, v54
	v_cvt_pk_bf16_f32 v30, v29, s0
	ds_write_b16 v191, v30 offset:2832
	v_mul_f32_e32 v30, 0xbfb8aa3b, v72
	v_exp_f32_e32 v30, v30
	v_mul_f32_e32 v29, v29, v50
	v_cvt_pk_bf16_f32 v29, v29, s0
	ds_write_b16 v191, v29 offset:20240
	v_mul_f32_e32 v29, v30, v52
	v_cvt_pk_bf16_f32 v30, v28, s0
	v_mul_f32_e32 v51, 0x3fb8aa3b, v74
	ds_write_b16 v191, v30 offset:3104
	v_mul_f32_e32 v30, 0xbfb8aa3b, v73
	v_exp_f32_e32 v51, v51
	v_exp_f32_e32 v30, v30
	v_mul_f32_e32 v28, v28, v50
	v_cvt_pk_bf16_f32 v28, v28, s0
	v_mul_f32_e32 v27, v27, v51
	ds_write_b16 v191, v28 offset:20512
	v_mul_f32_e32 v28, v30, v48
	v_cvt_pk_bf16_f32 v30, v27, s0
	v_mul_f32_e32 v48, 0x3fb8aa3b, v75
	ds_write_b16 v191, v30 offset:3376
	v_mul_f32_e32 v30, 0xbfb8aa3b, v74
	v_exp_f32_e32 v48, v48
	v_exp_f32_e32 v30, v30
	v_mul_f32_e32 v27, v27, v50
	v_cvt_pk_bf16_f32 v27, v27, s0
	v_mul_f32_e32 v25, v25, v48
	ds_write_b16 v191, v27 offset:20784
	v_mul_f32_e32 v27, v30, v47
	v_cvt_pk_bf16_f32 v30, v25, s0
	v_mul_f32_e32 v47, 0x3fb8aa3b, v76
	ds_write_b16 v191, v30 offset:3648
	v_mul_f32_e32 v30, 0xbfb8aa3b, v75
	v_exp_f32_e32 v47, v47
	v_exp_f32_e32 v30, v30
	v_mul_f32_e32 v25, v25, v50
	v_cvt_pk_bf16_f32 v25, v25, s0
	v_mul_f32_e32 v24, v24, v47
	ds_write_b16 v191, v25 offset:21056
	v_mul_f32_e32 v25, v30, v45
	v_cvt_pk_bf16_f32 v30, v24, s0
	v_mul_f32_e32 v45, 0x3fb8aa3b, v77
	ds_write_b16 v191, v30 offset:3920
	v_mul_f32_e32 v30, 0xbfb8aa3b, v76
	v_exp_f32_e32 v45, v45
	v_exp_f32_e32 v30, v30
	v_mul_f32_e32 v24, v24, v50
	v_cvt_pk_bf16_f32 v24, v24, s0
	v_mul_f32_e32 v23, v23, v45
	ds_write_b16 v191, v24 offset:21328
	v_mul_f32_e32 v24, v30, v43
	v_cvt_pk_bf16_f32 v30, v23, s0
	v_mul_f32_e32 v43, 0x3fb8aa3b, v78
	ds_write_b16 v191, v30 offset:4192
	v_mul_f32_e32 v30, 0xbfb8aa3b, v77
	v_exp_f32_e32 v43, v43
	v_exp_f32_e32 v30, v30
	v_mul_f32_e32 v23, v23, v50
	v_cvt_pk_bf16_f32 v23, v23, s0
	v_mul_f32_e32 v22, v22, v43
	ds_write_b16 v191, v23 offset:21600
	v_mul_f32_e32 v23, v30, v41
	v_cvt_pk_bf16_f32 v30, v22, s0
	v_mul_f32_e32 v41, 0x3fb8aa3b, v79
	ds_write_b16 v191, v30 offset:4464
	v_mul_f32_e32 v30, 0xbfb8aa3b, v78
	v_exp_f32_e32 v41, v41
	v_exp_f32_e32 v30, v30
	v_mul_f32_e32 v22, v22, v50
	v_cvt_pk_bf16_f32 v22, v22, s0
	v_mul_f32_e32 v26, v26, v41
	ds_write_b16 v191, v22 offset:21872
	v_mul_f32_e32 v22, v30, v39
	v_cvt_pk_bf16_f32 v30, v26, s0
	ds_write_b16 v191, v30 offset:4736
	v_mul_f32_e32 v30, 0xbfb8aa3b, v79
	v_exp_f32_e32 v30, v30
	v_mul_f32_e32 v39, 0x3fb8aa3b, v80
	v_exp_f32_e32 v39, v39
	v_mul_f32_e32 v26, v26, v50
	v_cvt_pk_bf16_f32 v26, v26, s0
	ds_write_b16 v191, v26 offset:22144
	v_mul_f32_e32 v26, v30, v46
	v_mul_f32_e32 v30, 0x3db504f3, v37
	v_mul_f32_e32 v30, v30, v39
	v_cvt_pk_bf16_f32 v37, v30, s0
	v_mul_f32_e32 v39, 0x3fb8aa3b, v81
	ds_write_b16 v191, v37 offset:5008
	v_mul_f32_e32 v37, 0xbfb8aa3b, v80
	v_exp_f32_e32 v39, v39
	v_exp_f32_e32 v37, v37
	v_mul_f32_e32 v30, v30, v50
	v_cvt_pk_bf16_f32 v30, v30, s0
	v_mul_f32_e32 v36, v36, v39
	ds_write_b16 v191, v30 offset:22416
	v_mul_f32_e32 v30, v37, v44
	v_cvt_pk_bf16_f32 v37, v36, s0
	v_mul_f32_e32 v39, 0x3fb8aa3b, v82
	ds_write_b16 v191, v37 offset:5280
	v_mul_f32_e32 v37, 0xbfb8aa3b, v81
	v_exp_f32_e32 v39, v39
	v_exp_f32_e32 v37, v37
	v_mul_f32_e32 v36, v36, v50
	v_cvt_pk_bf16_f32 v36, v36, s0
	v_mul_f32_e32 v35, v35, v39
	ds_write_b16 v191, v36 offset:22688
	v_mul_f32_e32 v36, v37, v42
	v_cvt_pk_bf16_f32 v37, v35, s0
	v_mul_f32_e32 v39, 0x3fb8aa3b, v83
	ds_write_b16 v191, v37 offset:5552
	v_mul_f32_e32 v37, 0xbfb8aa3b, v82
	v_exp_f32_e32 v39, v39
	v_exp_f32_e32 v37, v37
	v_mul_f32_e32 v35, v35, v50
	v_cvt_pk_bf16_f32 v35, v35, s0
	v_mul_f32_e32 v34, v34, v39
	ds_write_b16 v191, v35 offset:22960
	v_mul_f32_e32 v35, v37, v40
	v_cvt_pk_bf16_f32 v37, v34, s0
	v_mul_f32_e32 v39, 0x3fb8aa3b, v84
	ds_write_b16 v191, v37 offset:5824
	v_mul_f32_e32 v37, 0xbfb8aa3b, v83
	v_exp_f32_e32 v39, v39
	v_exp_f32_e32 v37, v37
	v_mul_f32_e32 v34, v34, v50
	v_cvt_pk_bf16_f32 v34, v34, s0
	v_mul_f32_e32 v33, v33, v39
	ds_write_b16 v191, v34 offset:23232
	v_mul_f32_e32 v34, v37, v38
	v_cvt_pk_bf16_f32 v37, v33, s0
	v_mul_f32_e32 v38, 0x3fb8aa3b, v55
	ds_write_b16 v191, v37 offset:6096
	v_mul_f32_e32 v37, 0xbfb8aa3b, v84
	v_exp_f32_e32 v38, v38
	v_exp_f32_e32 v37, v37
	v_mul_f32_e32 v33, v33, v50
	v_cvt_pk_bf16_f32 v33, v33, s0
	v_mul_f32_e32 v32, v32, v38
	ds_write_b16 v191, v33 offset:23504
	v_mul_f32_e32 v33, v37, v58
	v_cvt_pk_bf16_f32 v37, v32, s0
	v_mul_f32_e32 v38, 0x3fb8aa3b, v53
	ds_write_b16 v191, v37 offset:6368
	v_mul_f32_e32 v37, 0xbfb8aa3b, v55
	v_exp_f32_e32 v38, v38
	v_exp_f32_e32 v37, v37
	v_mul_f32_e32 v32, v32, v50
	v_cvt_pk_bf16_f32 v32, v32, s0
	v_mul_f32_e32 v31, v31, v38
	ds_write_b16 v191, v32 offset:23776
	v_mul_f32_e32 v32, v37, v59
	v_cvt_pk_bf16_f32 v37, v31, s0
	ds_write_b16 v191, v37 offset:6640
	v_mul_f32_e32 v37, 0xbfb8aa3b, v53
	v_exp_f32_e32 v37, v37
	v_mul_f32_e32 v31, v50, v31
	v_cvt_pk_bf16_f32 v31, v31, s0
	ds_write_b16 v191, v31 offset:24048
	v_mul_f32_e32 v31, v37, v60
	s_and_saveexec_b64 s[0:1], s[2:3]
	s_cbranch_execnz .LBB0_1394
	s_or_b64 exec, exec, s[0:1]
	s_and_saveexec_b64 s[0:1], s[4:5]
	s_cbranch_execnz .LBB0_1395

.LBB0_1367:
	s_and_b64 vcc, exec, s[0:1]
	s_cbranch_vccz .LBB0_1338
	s_add_i32 s24, s46, s37
	s_add_i32 s38, s24, 0xffffec00
	s_ashr_i32 s39, s38, 31
	s_lshl_b32 s69, s20, 6
	v_or_b32_e32 v20, s69, v135
	s_lshl_b64 s[40:41], s[38:39], 1
	v_lshl_add_u64 v[2:3], v[146:147], 0, s[40:41]
	v_or_b32_e32 v6, 1, v20
	v_mad_i64_i32 v[4:5], s[0:1], v20, s53, v[2:3]
	v_mad_i64_i32 v[6:7], s[0:1], v6, s53, v[2:3]
	v_or_b32_e32 v8, 2, v20
	v_or_b32_e32 v10, 3, v20
	v_or_b32_e32 v12, 4, v20
	v_or_b32_e32 v14, 5, v20
	v_or_b32_e32 v16, 6, v20
	v_or_b32_e32 v18, 7, v20
	v_mad_i64_i32 v[8:9], s[0:1], v8, s53, v[2:3]
	v_mad_i64_i32 v[10:11], s[0:1], v10, s53, v[2:3]
	v_mad_i64_i32 v[12:13], s[0:1], v12, s53, v[2:3]
	v_mad_i64_i32 v[14:15], s[0:1], v14, s53, v[2:3]
	v_mad_i64_i32 v[16:17], s[0:1], v16, s53, v[2:3]
	v_mad_i64_i32 v[18:19], s[0:1], v18, s53, v[2:3]
	global_load_ushort v21, v[4:5], off
	global_load_ushort v22, v[6:7], off
	global_load_ushort v23, v[8:9], off
	global_load_ushort v24, v[10:11], off
	global_load_ushort v25, v[12:13], off
	global_load_ushort v26, v[14:15], off
	global_load_ushort v27, v[16:17], off
	global_load_ushort v28, v[18:19], off
	v_or_b32_e32 v4, 8, v20
	v_or_b32_e32 v6, 9, v20
	v_mad_i64_i32 v[4:5], s[0:1], v4, s53, v[2:3]
	v_mad_i64_i32 v[6:7], s[0:1], v6, s53, v[2:3]
	v_or_b32_e32 v8, 10, v20
	v_or_b32_e32 v10, 11, v20
	v_or_b32_e32 v12, 12, v20
	v_or_b32_e32 v14, 13, v20
	v_or_b32_e32 v16, 14, v20
	v_or_b32_e32 v18, 15, v20
	v_mad_i64_i32 v[8:9], s[0:1], v8, s53, v[2:3]
	v_mad_i64_i32 v[10:11], s[0:1], v10, s53, v[2:3]
	v_mad_i64_i32 v[12:13], s[0:1], v12, s53, v[2:3]
	v_mad_i64_i32 v[14:15], s[0:1], v14, s53, v[2:3]
	v_mad_i64_i32 v[16:17], s[0:1], v16, s53, v[2:3]
	v_mad_i64_i32 v[2:3], s[0:1], v18, s53, v[2:3]
	global_load_ushort v20, v[4:5], off
	global_load_ushort v29, v[6:7], off
	global_load_ushort v30, v[8:9], off
	global_load_ushort v31, v[10:11], off
	global_load_ushort v32, v[12:13], off
	global_load_ushort v33, v[14:15], off
	global_load_ushort v34, v[16:17], off
	global_load_ushort v35, v[2:3], off
	v_add_u32_e32 v6, s24, v134
	v_add_u32_e32 v2, 0xffffec00, v6
	v_readlane_b32 s72, v255, 13
	v_ashrrev_i32_e32 v3, 31, v2
	v_readlane_b32 s76, v255, 17
	v_readlane_b32 s77, v255, 18
	v_or_b32_e32 v38, s69, v188
	v_mov_b64_e32 v[74:75], s[26:27]
	v_lshl_add_u64 v[2:3], v[2:3], 2, s[76:77]
	v_add_co_u32_e32 v4, vcc, s48, v2
	v_or_b32_e32 v10, 3, v38
	s_nop 0
	v_addc_co_u32_e32 v5, vcc, 0, v3, vcc
	global_load_dword v36, v[2:3], off
	global_load_dword v37, v[4:5], off
	v_add_u32_e32 v2, 0xfffff000, v6
	v_ashrrev_i32_e32 v3, 31, v2
	v_or_b32_e32 v12, 4, v38
	v_or_b32_e32 v14, 5, v38
	v_mad_i64_i32 v[4:5], s[0:1], v38, s53, v[74:75]
	v_lshlrev_b64 v[2:3], 1, v[2:3]
	v_or_b32_e32 v6, 1, v38
	v_or_b32_e32 v8, 2, v38
	v_mad_i64_i32 v[10:11], s[0:1], v10, s53, v[74:75]
	v_mad_i64_i32 v[12:13], s[0:1], v12, s53, v[74:75]
	v_mad_i64_i32 v[14:15], s[0:1], v14, s53, v[74:75]
	v_or_b32_e32 v16, 6, v38
	v_or_b32_e32 v18, 7, v38
	v_lshl_add_u64 v[4:5], v[4:5], 0, v[2:3]
	v_mad_i64_i32 v[6:7], s[0:1], v6, s53, v[74:75]
	v_mad_i64_i32 v[8:9], s[0:1], v8, s53, v[74:75]
	v_lshl_add_u64 v[10:11], v[10:11], 0, v[2:3]
	v_lshl_add_u64 v[12:13], v[12:13], 0, v[2:3]
	v_lshl_add_u64 v[14:15], v[14:15], 0, v[2:3]
	v_mad_i64_i32 v[16:17], s[0:1], v16, s53, v[74:75]
	v_mad_i64_i32 v[18:19], s[0:1], v18, s53, v[74:75]
	v_lshl_add_u64 v[6:7], v[6:7], 0, v[2:3]
	v_lshl_add_u64 v[8:9], v[8:9], 0, v[2:3]
	v_lshl_add_u64 v[16:17], v[16:17], 0, v[2:3]
	v_lshl_add_u64 v[18:19], v[18:19], 0, v[2:3]
	global_load_ushort v39, v[4:5], off
	global_load_ushort v40, v[6:7], off
	global_load_ushort v41, v[8:9], off
	global_load_ushort v42, v[10:11], off
	s_nop 0
	global_load_ushort v12, v[12:13], off
	s_nop 0
	global_load_ushort v13, v[14:15], off
	s_nop 0
	global_load_ushort v14, v[16:17], off
	global_load_ushort v15, v[18:19], off
	v_or_b32_e32 v4, 8, v38
	v_or_b32_e32 v10, 11, v38
	v_mad_i64_i32 v[4:5], s[0:1], v4, s53, v[74:75]
	v_or_b32_e32 v6, 9, v38
	v_or_b32_e32 v8, 10, v38
	v_mad_i64_i32 v[10:11], s[0:1], v10, s53, v[74:75]
	v_lshl_add_u64 v[4:5], v[4:5], 0, v[2:3]
	v_mad_i64_i32 v[6:7], s[0:1], v6, s53, v[74:75]
	v_mad_i64_i32 v[8:9], s[0:1], v8, s53, v[74:75]
	v_lshl_add_u64 v[10:11], v[10:11], 0, v[2:3]
	v_lshl_add_u64 v[6:7], v[6:7], 0, v[2:3]
	v_lshl_add_u64 v[8:9], v[8:9], 0, v[2:3]
	global_load_ushort v16, v[4:5], off
	global_load_ushort v17, v[6:7], off
	global_load_ushort v18, v[8:9], off
	s_nop 0
	global_load_ushort v10, v[10:11], off
	v_or_b32_e32 v4, 12, v38
	v_or_b32_e32 v6, 13, v38
	v_mad_i64_i32 v[4:5], s[0:1], v4, s53, v[74:75]
	v_mad_i64_i32 v[6:7], s[0:1], v6, s53, v[74:75]
	v_lshl_add_u64 v[4:5], v[4:5], 0, v[2:3]
	v_lshl_add_u64 v[6:7], v[6:7], 0, v[2:3]
	global_load_ushort v19, v[4:5], off
	global_load_ushort v43, v[6:7], off
	v_or_b32_e32 v4, 14, v38
	v_or_b32_e32 v6, 15, v38
	v_mad_i64_i32 v[4:5], s[0:1], v4, s53, v[74:75]
	v_mad_i64_i32 v[6:7], s[0:1], v6, s53, v[74:75]
	s_ashr_i32 s21, s20, 31
	s_ashr_i32 s37, s36, 31
	s_lshl_b64 s[0:1], s[20:21], 18
	s_lshl_b64 s[20:21], s[36:37], 15
	s_add_u32 s0, s90, s0
	v_lshl_add_u64 v[4:5], v[4:5], 0, v[2:3]
	s_addc_u32 s1, s91, s1
	v_lshl_add_u64 v[2:3], v[6:7], 0, v[2:3]
	global_load_ushort v38, v[4:5], off
	global_load_ushort v44, v[2:3], off
	s_waitcnt vmcnt(0)
	v_lshlrev_b32_e32 v93, 16, v20
	v_lshlrev_b32_e32 v98, 16, v24
	s_add_u32 s36, s0, s20
	s_addc_u32 s37, s1, s21
	v_sub_f32_e32 v4, v36, v37
	v_mul_f32_e32 v4, 0x3fb8aa3b, v4
	s_mul_hi_i32 s0, s69, 0x3a00
	s_add_u32 s20, s26, s68
	v_exp_f32_e32 v11, v4
	s_addc_u32 s21, s27, s0
	s_lshl_b64 s[0:1], s[24:25], 1
	s_add_u32 s0, s20, s0
	v_lshlrev_b32_e32 v97, 16, v25
	s_addc_u32 s1, s21, s1
	v_mov_b32_e32 v153, v137
	v_lshlrev_b32_e32 v96, 16, v26
	v_lshl_add_u64 v[2:3], s[0:1], 0, v[152:153]
	v_mov_b32_e32 v155, v137
	v_add_f32_e32 v11, 1.0, v11
	v_lshl_add_u64 v[2:3], v[2:3], 0, v[154:155]
	v_rcp_f32_e32 v11, v11
	v_add_co_u32_e32 v6, vcc, s55, v2
	v_lshlrev_b32_e32 v94, 16, v28
	s_nop 0
	v_addc_co_u32_e32 v7, vcc, 0, v3, vcc
	v_lshlrev_b32_e32 v101, 16, v21
	v_lshlrev_b32_e32 v91, 16, v30
	v_lshlrev_b32_e32 v90, 16, v31
	v_lshlrev_b32_e32 v100, 16, v22
	v_lshlrev_b32_e32 v99, 16, v23
	v_lshlrev_b32_e32 v20, 16, v39
	v_cmp_le_f32_e32 vcc, 0, v20
	v_lshlrev_b32_e32 v21, 16, v40
	v_mul_f32_e64 v30, |v21|, s60
	v_lshlrev_b32_e32 v24, 16, v12
	v_mul_f32_e64 v12, |v20|, s60
	v_exp_f32_e32 v12, v12
	v_exp_f32_e32 v30, v30
	v_lshlrev_b32_e32 v22, 16, v41
	v_lshlrev_b32_e32 v23, 16, v42
	v_lshlrev_b32_e32 v13, 16, v13
	v_add_f32_e32 v31, 1.0, v30
	v_rcp_f32_e32 v31, v31
	v_lshlrev_b32_e32 v14, 16, v14
	v_lshlrev_b32_e32 v15, 16, v15
	v_lshlrev_b32_e32 v95, 16, v27
	v_lshlrev_b32_e32 v92, 16, v29
	global_load_dwordx4 v[2:5], v[2:3], off
	s_nop 0
	global_load_dwordx4 v[6:9], v[6:7], off offset:2560
	v_readfirstlane_b32 s33, v0
	v_lshlrev_b32_e32 v136, 1, v140
	v_mov_b32_e32 v85, v137
	v_lshlrev_b32_e32 v16, 16, v16
	v_lshlrev_b32_e32 v17, 16, v17
	v_lshlrev_b32_e32 v18, 16, v18
	v_lshlrev_b32_e32 v25, 16, v10
	v_add_f32_e32 v10, 1.0, v12
	v_rcp_f32_e32 v26, v10
	v_sub_f32_e32 v10, 1.0, v11
	v_mov_b32_e32 v157, v137
	v_lshlrev_b32_e32 v89, 16, v32
	v_mul_f32_e32 v28, v12, v26
	v_cndmask_b32_e32 v12, v28, v26, vcc
	v_fma_f32 v12, v10, v12, v11
	v_cmp_gt_f32_e64 s[0:1], s61, v12
	v_cndmask_b32_e32 v26, v26, v28, vcc
	v_mul_f32_e32 v102, v10, v26
	v_cndmask_b32_e64 v20, 0, 32, s[0:1]
	v_ldexp_f32 v12, v12, v20
	v_log_f32_e32 v20, v12
	v_lshlrev_b32_e32 v19, 16, v19
	v_lshlrev_b32_e32 v27, 16, v43
	v_lshlrev_b32_e32 v88, 16, v33
	v_mul_f32_e32 v28, 0x3f317217, v20
	v_fma_f32 v28, v20, s62, -v28
	v_fmac_f32_e32 v28, 0x3377d1cf, v20
	v_fmac_f32_e32 v28, 0x3f317217, v20
	v_cmp_lt_f32_e64 vcc, |v20|, s63
	v_lshlrev_b32_e32 v87, 16, v34
	s_waitcnt vmcnt(3)
	v_lshlrev_b32_e32 v29, 16, v38
	v_cndmask_b32_e32 v20, v20, v28, vcc
	v_cndmask_b32_e64 v28, 0, v195, s[0:1]
	v_sub_f32_e32 v20, v20, v28
	v_mul_f32_e32 v28, v30, v31
	v_cmp_le_f32_e32 vcc, 0, v21
	v_add_f32_e32 v103, 0, v20
	s_waitcnt vmcnt(2)
	v_lshlrev_b32_e32 v12, 16, v44
	v_cndmask_b32_e32 v21, v28, v31, vcc
	v_fma_f32 v21, v10, v21, v11
	v_cmp_gt_f32_e64 s[0:1], s61, v21
	v_cndmask_b32_e32 v20, v31, v28, vcc
	v_mul_f32_e64 v28, |v22|, s60
	v_cndmask_b32_e64 v30, 0, 32, s[0:1]
	v_ldexp_f32 v21, v21, v30
	v_log_f32_e32 v21, v21
	v_exp_f32_e32 v28, v28
	v_mul_f32_e32 v104, v10, v20
	v_lshlrev_b32_e32 v86, 16, v35
	v_mul_f32_e32 v26, 0x3f317217, v21
	v_add_f32_e32 v30, 1.0, v28
	v_fma_f32 v26, v21, s62, -v26
	v_rcp_f32_e32 v30, v30
	v_fmac_f32_e32 v26, 0x3377d1cf, v21
	v_fmac_f32_e32 v26, 0x3f317217, v21
	v_cmp_lt_f32_e64 vcc, |v21|, s63
	v_mul_f32_e32 v101, 0x3db504f3, v101
	v_mul_f32_e32 v100, 0x3db504f3, v100
	v_cndmask_b32_e32 v21, v21, v26, vcc
	v_cndmask_b32_e64 v26, 0, v195, s[0:1]
	v_sub_f32_e32 v21, v21, v26
	v_mul_f32_e32 v26, v28, v30
	v_cmp_le_f32_e32 vcc, 0, v22
	v_add_f32_e32 v105, v103, v21
	v_mul_f32_e32 v99, 0x3db504f3, v99
	v_cndmask_b32_e32 v22, v26, v30, vcc
	v_fma_f32 v22, v10, v22, v11
	v_cmp_gt_f32_e64 s[0:1], s61, v22
	v_cndmask_b32_e32 v20, v30, v26, vcc
	v_mul_f32_e64 v26, |v23|, s60
	v_cndmask_b32_e64 v28, 0, 32, s[0:1]
	v_ldexp_f32 v22, v22, v28
	v_log_f32_e32 v22, v22
	v_exp_f32_e32 v26, v26
	v_mul_f32_e32 v106, v10, v20
	v_mul_f32_e32 v98, 0x3db504f3, v98
	v_mul_f32_e32 v21, 0x3f317217, v22
	v_add_f32_e32 v28, 1.0, v26
	v_fma_f32 v21, v22, s62, -v21
	v_rcp_f32_e32 v28, v28
	v_fmac_f32_e32 v21, 0x3377d1cf, v22
	v_fmac_f32_e32 v21, 0x3f317217, v22
	v_cmp_lt_f32_e64 vcc, |v22|, s63
	v_mul_f32_e32 v97, 0x3db504f3, v97
	v_mul_f32_e32 v96, 0x3db504f3, v96
	v_cndmask_b32_e32 v21, v22, v21, vcc
	v_cndmask_b32_e64 v22, 0, v195, s[0:1]
	v_sub_f32_e32 v21, v21, v22
	v_mul_f32_e32 v22, v26, v28
	v_cmp_le_f32_e32 vcc, 0, v23
	v_add_f32_e32 v107, v105, v21
	v_mul_f32_e32 v95, 0x3db504f3, v95
	v_cndmask_b32_e32 v23, v22, v28, vcc
	v_fma_f32 v23, v10, v23, v11
	v_cmp_gt_f32_e64 s[0:1], s61, v23
	v_cndmask_b32_e32 v20, v28, v22, vcc
	v_mul_f32_e64 v22, |v24|, s60
	v_cndmask_b32_e64 v26, 0, 32, s[0:1]
	v_ldexp_f32 v23, v23, v26
	v_exp_f32_e32 v22, v22
	v_log_f32_e32 v23, v23
	v_mul_f32_e32 v108, v10, v20
	v_mul_f32_e32 v94, 0x3db504f3, v94
	v_add_f32_e32 v26, 1.0, v22
	v_mul_f32_e32 v21, 0x3f317217, v23
	v_rcp_f32_e32 v26, v26
	v_fma_f32 v21, v23, s62, -v21
	v_fmac_f32_e32 v21, 0x3377d1cf, v23
	v_fmac_f32_e32 v21, 0x3f317217, v23
	v_cmp_lt_f32_e64 vcc, |v23|, s63
	v_mul_f32_e32 v22, v22, v26
	v_mul_f32_e32 v93, 0x3db504f3, v93
	v_cndmask_b32_e32 v21, v23, v21, vcc
	v_cndmask_b32_e64 v23, 0, v195, s[0:1]
	v_cmp_le_f32_e32 vcc, 0, v24
	v_sub_f32_e32 v21, v21, v23
	v_add_f32_e32 v109, v107, v21
	v_cndmask_b32_e32 v23, v22, v26, vcc
	v_fma_f32 v23, v10, v23, v11
	v_cmp_gt_f32_e64 s[0:1], s61, v23
	v_cndmask_b32_e32 v20, v26, v22, vcc
	v_mul_f32_e64 v22, |v13|, s60
	v_cndmask_b32_e64 v24, 0, 32, s[0:1]
	v_ldexp_f32 v23, v23, v24
	v_exp_f32_e32 v22, v22
	v_log_f32_e32 v23, v23
	v_mul_f32_e32 v110, v10, v20
	v_mul_f32_e32 v92, 0x3db504f3, v92
	v_add_f32_e32 v24, 1.0, v22
	v_mul_f32_e32 v21, 0x3f317217, v23
	v_rcp_f32_e32 v24, v24
	v_fma_f32 v21, v23, s62, -v21
	v_fmac_f32_e32 v21, 0x3377d1cf, v23
	v_fmac_f32_e32 v21, 0x3f317217, v23
	v_cmp_lt_f32_e64 vcc, |v23|, s63
	v_mul_f32_e32 v22, v22, v24
	v_mul_f32_e32 v91, 0x3db504f3, v91
	v_cndmask_b32_e32 v21, v23, v21, vcc
	v_cmp_le_f32_e32 vcc, 0, v13
	v_cndmask_b32_e64 v23, 0, v195, s[0:1]
	v_sub_f32_e32 v21, v21, v23
	v_cndmask_b32_e32 v13, v22, v24, vcc
	v_fma_f32 v13, v10, v13, v11
	v_cmp_gt_f32_e64 s[0:1], s61, v13
	v_cndmask_b32_e32 v20, v24, v22, vcc
	v_mul_f32_e64 v22, |v14|, s60
	v_cndmask_b32_e64 v23, 0, 32, s[0:1]
	v_ldexp_f32 v13, v13, v23
	v_log_f32_e32 v13, v13
	v_exp_f32_e32 v22, v22
	v_add_f32_e32 v111, v109, v21
	v_mul_f32_e32 v112, v10, v20
	v_mul_f32_e32 v21, 0x3f317217, v13
	v_add_f32_e32 v23, 1.0, v22
	v_fma_f32 v21, v13, s62, -v21
	v_rcp_f32_e32 v23, v23
	v_fmac_f32_e32 v21, 0x3377d1cf, v13
	v_fmac_f32_e32 v21, 0x3f317217, v13
	v_cmp_lt_f32_e64 vcc, |v13|, s63
	v_mul_f32_e32 v90, 0x3db504f3, v90
	v_mul_f32_e32 v89, 0x3db504f3, v89
	v_cndmask_b32_e32 v13, v13, v21, vcc
	v_cndmask_b32_e64 v21, 0, v195, s[0:1]
	v_sub_f32_e32 v13, v13, v21
	v_mul_f32_e32 v21, v22, v23
	v_cmp_le_f32_e32 vcc, 0, v14
	v_add_f32_e32 v113, v111, v13
	v_mul_f32_e32 v88, 0x3db504f3, v88
	v_cndmask_b32_e32 v14, v21, v23, vcc
	v_fma_f32 v14, v10, v14, v11
	v_cmp_gt_f32_e64 s[0:1], s61, v14
	v_cndmask_b32_e32 v13, v23, v21, vcc
	v_mul_f32_e64 v21, |v15|, s60
	v_cndmask_b32_e64 v22, 0, 32, s[0:1]
	v_ldexp_f32 v14, v14, v22
	v_log_f32_e32 v14, v14
	v_exp_f32_e32 v21, v21
	v_mul_f32_e32 v121, v10, v13
	v_mul_f32_e32 v87, 0x3db504f3, v87
	v_mul_f32_e32 v20, 0x3f317217, v14
	v_add_f32_e32 v22, 1.0, v21
	v_fma_f32 v20, v14, s62, -v20
	v_rcp_f32_e32 v22, v22
	v_fmac_f32_e32 v20, 0x3377d1cf, v14
	v_fmac_f32_e32 v20, 0x3f317217, v14
	v_cmp_lt_f32_e64 vcc, |v14|, s63
	v_mul_f32_e32 v86, 0x3db504f3, v86
	v_readlane_b32 s73, v255, 14
	v_cndmask_b32_e32 v14, v14, v20, vcc
	v_cndmask_b32_e64 v20, 0, v195, s[0:1]
	v_sub_f32_e32 v14, v14, v20
	v_mul_f32_e32 v20, v21, v22
	v_cmp_le_f32_e32 vcc, 0, v15
	v_add_f32_e32 v120, v113, v14
	v_readlane_b32 s74, v255, 15
	v_cndmask_b32_e32 v15, v20, v22, vcc
	v_fma_f32 v15, v10, v15, v11
	v_cmp_gt_f32_e64 s[0:1], s61, v15
	v_cndmask_b32_e32 v13, v22, v20, vcc
	v_mul_f32_e64 v20, |v16|, s60
	v_cndmask_b32_e64 v21, 0, 32, s[0:1]
	v_ldexp_f32 v15, v15, v21
	v_log_f32_e32 v15, v15
	v_exp_f32_e32 v20, v20
	v_mul_f32_e32 v123, v10, v13
	v_readlane_b32 s75, v255, 16
	v_mul_f32_e32 v14, 0x3f317217, v15
	v_add_f32_e32 v21, 1.0, v20
	v_fma_f32 v14, v15, s62, -v14
	v_rcp_f32_e32 v21, v21
	v_fmac_f32_e32 v14, 0x3377d1cf, v15
	v_fmac_f32_e32 v14, 0x3f317217, v15
	v_cmp_lt_f32_e64 vcc, |v15|, s63
	v_readlane_b32 s78, v255, 19
	v_readlane_b32 s79, v255, 20
	v_cndmask_b32_e32 v14, v15, v14, vcc
	v_cndmask_b32_e64 v15, 0, v195, s[0:1]
	v_sub_f32_e32 v14, v14, v15
	v_mul_f32_e32 v15, v20, v21
	v_cmp_le_f32_e32 vcc, 0, v16
	v_add_f32_e32 v122, v120, v14
	v_readlane_b32 s80, v255, 21
	v_cndmask_b32_e32 v16, v15, v21, vcc
	v_fma_f32 v16, v10, v16, v11
	v_cmp_gt_f32_e64 s[0:1], s61, v16
	v_cndmask_b32_e32 v13, v21, v15, vcc
	v_mul_f32_e64 v15, |v17|, s60
	v_cndmask_b32_e64 v20, 0, 32, s[0:1]
	v_ldexp_f32 v16, v16, v20
	v_exp_f32_e32 v15, v15
	v_log_f32_e32 v16, v16
	v_mul_f32_e32 v125, v10, v13
	v_readlane_b32 s81, v255, 22
	v_add_f32_e32 v20, 1.0, v15
	v_mul_f32_e32 v14, 0x3f317217, v16
	v_rcp_f32_e32 v20, v20
	v_fma_f32 v14, v16, s62, -v14
	v_fmac_f32_e32 v14, 0x3377d1cf, v16
	v_fmac_f32_e32 v14, 0x3f317217, v16
	v_cmp_lt_f32_e64 vcc, |v16|, s63
	v_mul_f32_e32 v15, v15, v20
	v_readlane_b32 s82, v255, 23
	v_cndmask_b32_e32 v14, v16, v14, vcc
	v_cndmask_b32_e64 v16, 0, v195, s[0:1]
	v_cmp_le_f32_e32 vcc, 0, v17
	v_sub_f32_e32 v14, v14, v16
	v_add_f32_e32 v124, v122, v14
	v_cndmask_b32_e32 v16, v15, v20, vcc
	v_fma_f32 v16, v10, v16, v11
	v_cmp_gt_f32_e64 s[0:1], s61, v16
	v_cndmask_b32_e32 v13, v20, v15, vcc
	v_mul_f32_e64 v15, |v18|, s60
	v_cndmask_b32_e64 v17, 0, 32, s[0:1]
	v_ldexp_f32 v16, v16, v17
	v_exp_f32_e32 v15, v15
	v_log_f32_e32 v16, v16
	v_mul_f32_e32 v127, v10, v13
	v_readlane_b32 s83, v255, 24
	v_add_f32_e32 v17, 1.0, v15
	v_mul_f32_e32 v14, 0x3f317217, v16
	v_rcp_f32_e32 v17, v17
	v_fma_f32 v14, v16, s62, -v14
	v_fmac_f32_e32 v14, 0x3377d1cf, v16
	v_fmac_f32_e32 v14, 0x3f317217, v16
	v_cmp_lt_f32_e64 vcc, |v16|, s63
	v_mul_f32_e32 v15, v15, v17
	v_readlane_b32 s84, v255, 25
	v_cndmask_b32_e32 v14, v16, v14, vcc
	v_cndmask_b32_e64 v16, 0, v195, s[0:1]
	v_cmp_le_f32_e32 vcc, 0, v18
	v_sub_f32_e32 v14, v14, v16
	v_add_f32_e32 v126, v124, v14
	v_cndmask_b32_e32 v16, v15, v17, vcc
	v_fma_f32 v16, v10, v16, v11
	v_cmp_gt_f32_e64 s[0:1], s61, v16
	v_cndmask_b32_e32 v13, v17, v15, vcc
	v_mul_f32_e64 v15, |v25|, s60
	v_cndmask_b32_e64 v18, 0, 32, s[0:1]
	v_ldexp_f32 v16, v16, v18
	v_exp_f32_e32 v15, v15
	v_log_f32_e32 v16, v16
	v_mul_f32_e32 v129, v10, v13
	v_readlane_b32 s85, v255, 26
	v_add_f32_e32 v17, 1.0, v15
	v_mul_f32_e32 v14, 0x3f317217, v16
	v_rcp_f32_e32 v17, v17
	v_fma_f32 v14, v16, s62, -v14
	v_fmac_f32_e32 v14, 0x3377d1cf, v16
	v_fmac_f32_e32 v14, 0x3f317217, v16
	v_cmp_lt_f32_e64 vcc, |v16|, s63
	v_mul_f32_e32 v15, v15, v17
	v_readlane_b32 s86, v255, 27
	v_cndmask_b32_e32 v14, v16, v14, vcc
	v_cndmask_b32_e64 v16, 0, v195, s[0:1]
	v_cmp_le_f32_e32 vcc, 0, v25
	v_sub_f32_e32 v14, v14, v16
	v_add_f32_e32 v128, v126, v14
	v_cndmask_b32_e32 v16, v15, v17, vcc
	v_fma_f32 v16, v10, v16, v11
	v_cmp_gt_f32_e64 s[0:1], s61, v16
	v_cndmask_b32_e32 v13, v17, v15, vcc
	v_mul_f32_e64 v15, |v19|, s60
	v_cndmask_b32_e64 v18, 0, 32, s[0:1]
	v_ldexp_f32 v16, v16, v18
	v_exp_f32_e32 v15, v15
	v_log_f32_e32 v16, v16
	v_mul_f32_e32 v131, v10, v13
	v_readlane_b32 s87, v255, 28
	v_add_f32_e32 v17, 1.0, v15
	v_mul_f32_e32 v14, 0x3f317217, v16
	v_rcp_f32_e32 v17, v17
	v_fma_f32 v14, v16, s62, -v14
	v_fmac_f32_e32 v14, 0x3377d1cf, v16
	v_fmac_f32_e32 v14, 0x3f317217, v16
	v_cmp_lt_f32_e64 vcc, |v16|, s63
	v_mul_f32_e32 v15, v15, v17
	s_nop 0
	v_cndmask_b32_e32 v14, v16, v14, vcc
	v_cndmask_b32_e64 v16, 0, v195, s[0:1]
	v_cmp_le_f32_e32 vcc, 0, v19
	v_sub_f32_e32 v14, v14, v16
	v_add_f32_e32 v130, v128, v14
	v_cndmask_b32_e32 v16, v15, v17, vcc
	v_fma_f32 v16, v10, v16, v11
	v_cmp_gt_f32_e64 s[0:1], s61, v16
	v_cndmask_b32_e32 v13, v17, v15, vcc
	v_mul_f32_e64 v15, |v27|, s60
	v_cndmask_b32_e64 v18, 0, 32, s[0:1]
	v_ldexp_f32 v16, v16, v18
	v_exp_f32_e32 v15, v15
	v_log_f32_e32 v16, v16
	v_mul_f32_e32 v133, v10, v13
	v_add_f32_e32 v17, 1.0, v15
	v_mul_f32_e32 v14, 0x3f317217, v16
	v_rcp_f32_e32 v17, v17
	v_fma_f32 v14, v16, s62, -v14
	v_fmac_f32_e32 v14, 0x3377d1cf, v16
	v_fmac_f32_e32 v14, 0x3f317217, v16
	v_cmp_lt_f32_e64 vcc, |v16|, s63
	v_mul_f32_e32 v15, v15, v17
	s_nop 0
	v_cndmask_b32_e32 v14, v16, v14, vcc
	v_cndmask_b32_e64 v16, 0, v195, s[0:1]
	v_cmp_le_f32_e32 vcc, 0, v27
	v_sub_f32_e32 v14, v14, v16
	v_add_f32_e32 v132, v130, v14
	v_cndmask_b32_e32 v16, v15, v17, vcc
	v_fma_f32 v16, v10, v16, v11
	v_cmp_gt_f32_e64 s[0:1], s61, v16
	v_cndmask_b32_e32 v13, v17, v15, vcc
	v_mul_f32_e64 v15, |v29|, s60
	v_cndmask_b32_e64 v18, 0, 32, s[0:1]
	v_ldexp_f32 v16, v16, v18
	v_log_f32_e32 v16, v16
	v_exp_f32_e32 v15, v15
	v_mul_f32_e32 v151, v10, v13
	v_mul_f32_e32 v14, 0x3f317217, v16
	v_add_f32_e32 v17, 1.0, v15
	v_fma_f32 v14, v16, s62, -v14
	v_rcp_f32_e32 v17, v17
	v_fmac_f32_e32 v14, 0x3377d1cf, v16
	v_fmac_f32_e32 v14, 0x3f317217, v16
	v_cmp_lt_f32_e64 vcc, |v16|, s63
	v_mul_f32_e32 v13, v15, v17
	s_nop 0
	v_cndmask_b32_e32 v14, v16, v14, vcc
	v_cndmask_b32_e64 v16, 0, v195, s[0:1]
	v_sub_f32_e32 v14, v14, v16
	v_cmp_le_f32_e32 vcc, 0, v29
	v_add_f32_e32 v149, v132, v14
	s_nop 0
	v_cndmask_b32_e32 v14, v13, v17, vcc
	v_fma_f32 v14, v10, v14, v11
	v_cmp_gt_f32_e64 s[0:1], s61, v14
	s_nop 1
	v_cndmask_b32_e64 v15, 0, 32, s[0:1]
	v_ldexp_f32 v14, v14, v15
	v_cndmask_b32_e32 v15, v17, v13, vcc
	v_mul_f32_e64 v13, |v12|, s60
	v_exp_f32_e32 v13, v13
	v_log_f32_e32 v14, v14
	v_mul_f32_e32 v158, v10, v15
	v_add_f32_e32 v17, 1.0, v13
	v_mul_f32_e32 v16, 0x3f317217, v14
	v_rcp_f32_e32 v17, v17
	v_fma_f32 v16, v14, s62, -v16
	v_fmac_f32_e32 v16, 0x3377d1cf, v14
	v_fmac_f32_e32 v16, 0x3f317217, v14
	v_cmp_lt_f32_e64 vcc, |v14|, s63
	s_nop 1
	v_cndmask_b32_e32 v14, v14, v16, vcc
	v_mul_f32_e32 v16, v13, v17
	v_cmp_le_f32_e32 vcc, 0, v12
	s_nop 1
	v_cndmask_b32_e32 v12, v16, v17, vcc
	v_fmac_f32_e32 v11, v10, v12
	v_cmp_gt_f32_e64 s[20:21], s61, v11
	s_nop 1
	v_cndmask_b32_e64 v12, 0, 32, s[20:21]
	v_ldexp_f32 v11, v11, v12
	v_log_f32_e32 v11, v11
	v_cndmask_b32_e64 v12, 0, v195, s[0:1]
	v_sub_f32_e32 v12, v14, v12
	v_add_f32_e32 v153, v149, v12
	v_mul_f32_e32 v12, 0x3f317217, v11
	v_fma_f32 v12, v11, s62, -v12
	v_fmac_f32_e32 v12, 0x3377d1cf, v11
	v_fmac_f32_e32 v12, 0x3f317217, v11
	v_cmp_lt_f32_e64 s[0:1], |v11|, s63
	s_nop 1
	v_cndmask_b32_e64 v11, v11, v12, s[0:1]
	v_cndmask_b32_e64 v12, 0, v195, s[20:21]
	v_sub_f32_e32 v11, v11, v12
	v_add_f32_e32 v155, v153, v11
	ds_write_b32 v141, v155
	s_waitcnt lgkmcnt(0)
	s_barrier
	ds_read2st64_b32 v[12:13], v143 offset1:2
	v_cndmask_b32_e32 v11, v17, v16, vcc
	s_lshr_b32 s0, s33, 2
	v_mul_f32_e32 v159, v10, v11
	s_and_b32 s68, s0, 0x3fffffc0
	v_lshl_add_u64 v[10:11], s[36:37], 0, v[136:137]
	s_bfe_u32 s37, s33, 0x20006
	ds_read2st64_b32 v[14:15], v143 offset0:4 offset1:6
	s_waitcnt lgkmcnt(1)
	v_add_f32_e32 v117, 0, v12
	v_or_b32_e32 v84, s68, v139
	s_lshl_b32 s36, s37, 4
	v_add_f32_e32 v115, v117, v13
	v_lshlrev_b64 v[12:13], 8, v[84:85]
	v_or_b32_e32 v85, s36, v139
	v_or_b32_e32 v76, s69, v85
	v_mad_i64_i32 v[82:83], s[0:1], v76, s53, v[74:75]
	v_lshl_add_u64 v[74:75], v[82:83], 0, s[40:41]
	s_waitcnt lgkmcnt(0)
	v_add_f32_e32 v114, v115, v14
	v_or_b32_e32 v136, 16, v84
	v_lshl_add_u64 v[74:75], v[74:75], 0, v[156:157]
	s_lshl_b32 s0, s68, 1
	s_mov_b32 s1, s25
	v_add_f32_e32 v116, v114, v15
	v_lshlrev_b64 v[14:15], 8, v[136:137]
	v_or_b32_e32 v136, 32, v84
	v_lshl_add_u64 v[74:75], v[74:75], 0, s[0:1]
	v_lshl_add_u64 v[22:23], v[10:11], 0, v[14:15]
	v_lshlrev_b64 v[14:15], 8, v[136:137]
	v_or_b32_e32 v136, 48, v84
	v_lshl_add_u64 v[118:119], v[74:75], 0, s[34:35]
	v_add_co_u32_e32 v74, vcc, s48, v74
	v_lshl_add_u64 v[26:27], v[10:11], 0, v[14:15]
	v_lshlrev_b64 v[14:15], 8, v[136:137]
	v_addc_co_u32_e32 v75, vcc, 0, v75, vcc
	v_lshl_add_u64 v[12:13], v[10:11], 0, v[12:13]
	v_lshl_add_u64 v[10:11], v[10:11], 0, v[14:15]
	v_cmp_eq_u32_e32 vcc, 1, v1
	s_mul_hi_u32 s99, s67, 0xaaaaaaab
	v_and_b32_e32 v236, 15, v0
	v_bfe_u32 v237, v0, 4, 2
	v_lshrrev_b32_e32 v238, 6, v0
	s_lshr_b32 s99, s99, 3
	s_mul_i32 s100, s99, 12
	s_sub_u32 s100, s67, s100
	s_lshl_b32 s101, s99, 3
	s_add_i32 s101, s101, s100
	s_lshl_b32 s101, s101, 15
	s_add_u32 s0, s90, s101
	s_addc_u32 s1, s91, 0
	v_lshlrev_b32_e32 v239, 8, v236
	v_lshl_add_u32 v239, v237, 4, v239
	v_lshl_add_u32 v239, v238, 12, v239
	global_load_dwordx4 v[200:203], v239, s[0:1]
	global_load_dwordx4 v[204:207], v239, s[0:1] offset:64
	global_load_dwordx4 v[208:211], v239, s[0:1] offset:128
	global_load_dwordx4 v[212:215], v239, s[0:1] offset:192
	s_mul_i32 s99, s99, 0xe8000
	s_lshl_b32 s101, s100, 8
	s_add_i32 s99, s99, s101
	s_addk_i32 s99, 7168
	v_mul_u32_u24_e32 v242, 0x3a00, v236
	v_lshl_add_u32 v242, v237, 3, v242
	v_lshl_add_u32 v242, v238, 5, v242
	v_add_u32_e32 v242, s99, v242
	v_mov_b32_e32 v243, 0
	s_mov_b64 s[98:99], 0x3a000
	v_lshl_add_u64 v[228:229], v[242:243], 0, s[26:27]
	v_lshl_add_u64 v[230:231], v[228:229], 0, s[98:99]
	v_lshl_add_u64 v[232:233], v[230:231], 0, s[98:99]
	v_lshl_add_u64 v[234:235], v[232:233], 0, s[98:99]
	global_load_dwordx2 v[216:217], v[228:229], off offset:-3072
	global_load_dwordx2 v[218:219], v[230:231], off offset:-3072
	global_load_dwordx2 v[220:221], v[232:233], off offset:-3072
	global_load_dwordx2 v[222:223], v[234:235], off offset:-3072
	v_readlane_b32 s98, v255, 19
	v_readlane_b32 s99, v255, 20
	s_lshl_b32 s101, s100, 9
	v_lshl_add_u32 v244, v237, 4, s101
	v_lshl_add_u32 v244, v238, 6, v244
	s_nop 3
	global_load_dwordx4 v[224:227], v244, s[98:99]
	v_cndmask_b32_e32 v118, 0, v117, vcc
	v_cmp_eq_u32_e32 vcc, 2, v1
	s_nop 1
	v_cndmask_b32_e32 v118, v118, v115, vcc
	v_cmp_eq_u32_e32 vcc, 3, v1
	s_nop 1
	v_cndmask_b32_e32 v118, v118, v114, vcc
	v_cmp_eq_u32_e32 vcc, 4, v1
	s_nop 1
	v_cndmask_b32_e32 v116, v118, v116, vcc
	v_mul_f32_e32 v118, 0x3fb8aa3b, v103
	v_exp_f32_e32 v118, v118
	v_mul_f32_e32 v119, 0x3fb8aa3b, v116
	v_exp_f32_e32 v119, v119
	v_mul_f32_e32 v103, 0xbfb8aa3b, v103
	v_mul_f32_e32 v101, v101, v118
	v_cvt_pk_bf16_f32 v118, v101, s0
	ds_write_b16 v191, v118 offset:2560
	v_mul_f32_e32 v118, 0x3fb8aa3b, v105
	v_exp_f32_e32 v118, v118
	v_exp_f32_e32 v103, v103
	v_mul_f32_e32 v101, v101, v119
	v_cvt_pk_bf16_f32 v101, v101, s0
	v_mul_f32_e32 v100, v100, v118
	ds_write_b16 v191, v101 offset:19968
	v_mul_f32_e32 v101, v102, v103
	v_cvt_pk_bf16_f32 v102, v100, s0
	v_mul_f32_e32 v103, 0x3fb8aa3b, v107
	ds_write_b16 v191, v102 offset:2832
	v_mul_f32_e32 v102, 0xbfb8aa3b, v105
	v_exp_f32_e32 v103, v103
	v_exp_f32_e32 v102, v102
	v_mul_f32_e32 v100, v100, v119
	v_cvt_pk_bf16_f32 v100, v100, s0
	v_mul_f32_e32 v99, v99, v103
	ds_write_b16 v191, v100 offset:20240
	v_mul_f32_e32 v100, v104, v102
	v_cvt_pk_bf16_f32 v102, v99, s0
	v_mul_f32_e32 v103, 0x3fb8aa3b, v109
	ds_write_b16 v191, v102 offset:3104
	v_mul_f32_e32 v102, 0xbfb8aa3b, v107
	v_exp_f32_e32 v103, v103
	v_exp_f32_e32 v102, v102
	v_mul_f32_e32 v99, v99, v119
	v_cvt_pk_bf16_f32 v99, v99, s0
	v_mul_f32_e32 v98, v98, v103
	ds_write_b16 v191, v99 offset:20512
	v_mul_f32_e32 v99, v106, v102
	v_cvt_pk_bf16_f32 v102, v98, s0
	v_mul_f32_e32 v103, 0x3fb8aa3b, v111
	ds_write_b16 v191, v102 offset:3376
	v_mul_f32_e32 v102, 0xbfb8aa3b, v109
	v_exp_f32_e32 v103, v103
	v_exp_f32_e32 v102, v102
	v_mul_f32_e32 v98, v98, v119
	v_cvt_pk_bf16_f32 v98, v98, s0
	v_mul_f32_e32 v97, v97, v103
	ds_write_b16 v191, v98 offset:20784
	v_mul_f32_e32 v98, v108, v102
	v_cvt_pk_bf16_f32 v102, v97, s0
	v_mul_f32_e32 v103, 0x3fb8aa3b, v113
	ds_write_b16 v191, v102 offset:3648
	v_mul_f32_e32 v102, 0xbfb8aa3b, v111
	v_exp_f32_e32 v103, v103
	v_exp_f32_e32 v102, v102
	v_mul_f32_e32 v97, v97, v119
	v_cvt_pk_bf16_f32 v97, v97, s0
	v_mul_f32_e32 v96, v96, v103
	ds_write_b16 v191, v97 offset:21056
	v_mul_f32_e32 v97, v110, v102
	v_cvt_pk_bf16_f32 v102, v96, s0
	v_mul_f32_e32 v103, 0x3fb8aa3b, v120
	ds_write_b16 v191, v102 offset:3920
	v_mul_f32_e32 v102, 0xbfb8aa3b, v113
	v_exp_f32_e32 v103, v103
	v_exp_f32_e32 v102, v102
	v_mul_f32_e32 v96, v96, v119
	v_cvt_pk_bf16_f32 v96, v96, s0
	v_mul_f32_e32 v95, v95, v103
	ds_write_b16 v191, v96 offset:21328
	v_mul_f32_e32 v96, v112, v102
	v_cvt_pk_bf16_f32 v102, v95, s0
	v_mul_f32_e32 v103, 0x3fb8aa3b, v122
	ds_write_b16 v191, v102 offset:4192
	v_mul_f32_e32 v102, 0xbfb8aa3b, v120
	v_exp_f32_e32 v103, v103
	v_exp_f32_e32 v102, v102
	v_mul_f32_e32 v95, v95, v119
	v_cvt_pk_bf16_f32 v95, v95, s0
	v_mul_f32_e32 v94, v94, v103
	ds_write_b16 v191, v95 offset:21600
	v_mul_f32_e32 v95, v121, v102
	v_cvt_pk_bf16_f32 v102, v94, s0
	v_mul_f32_e32 v103, 0x3fb8aa3b, v124
	ds_write_b16 v191, v102 offset:4464
	v_mul_f32_e32 v102, 0xbfb8aa3b, v122
	v_exp_f32_e32 v103, v103
	v_exp_f32_e32 v102, v102
	v_mul_f32_e32 v94, v94, v119
	v_cvt_pk_bf16_f32 v94, v94, s0
	v_mul_f32_e32 v93, v93, v103
	ds_write_b16 v191, v94 offset:21872
	v_mul_f32_e32 v94, v123, v102
	v_cvt_pk_bf16_f32 v102, v93, s0
	v_mul_f32_e32 v103, 0x3fb8aa3b, v126
	ds_write_b16 v191, v102 offset:4736
	v_mul_f32_e32 v102, 0xbfb8aa3b, v124
	v_exp_f32_e32 v103, v103
	v_exp_f32_e32 v102, v102
	v_mul_f32_e32 v93, v93, v119
	v_cvt_pk_bf16_f32 v93, v93, s0
	v_mul_f32_e32 v92, v92, v103
	ds_write_b16 v191, v93 offset:22144
	v_mul_f32_e32 v93, v125, v102
	v_cvt_pk_bf16_f32 v102, v92, s0
	v_mul_f32_e32 v103, 0x3fb8aa3b, v128
	ds_write_b16 v191, v102 offset:5008
	v_mul_f32_e32 v102, 0xbfb8aa3b, v126
	v_exp_f32_e32 v103, v103
	v_exp_f32_e32 v102, v102
	v_mul_f32_e32 v92, v92, v119
	v_cvt_pk_bf16_f32 v92, v92, s0
	v_mul_f32_e32 v91, v91, v103
	ds_write_b16 v191, v92 offset:22416
	v_mul_f32_e32 v92, v127, v102
	v_cvt_pk_bf16_f32 v102, v91, s0
	v_mul_f32_e32 v103, 0x3fb8aa3b, v130
	ds_write_b16 v191, v102 offset:5280
	v_mul_f32_e32 v102, 0xbfb8aa3b, v128
	v_exp_f32_e32 v103, v103
	v_exp_f32_e32 v102, v102
	v_mul_f32_e32 v91, v91, v119
	v_cvt_pk_bf16_f32 v91, v91, s0
	v_mul_f32_e32 v90, v90, v103
	ds_write_b16 v191, v91 offset:22688
	v_mul_f32_e32 v91, v129, v102
	v_cvt_pk_bf16_f32 v102, v90, s0
	v_mul_f32_e32 v103, 0x3fb8aa3b, v132
	ds_write_b16 v191, v102 offset:5552
	v_mul_f32_e32 v102, 0xbfb8aa3b, v130
	v_exp_f32_e32 v103, v103
	v_exp_f32_e32 v102, v102
	v_mul_f32_e32 v90, v119, v90
	v_cvt_pk_bf16_f32 v90, v90, s0
	v_mul_f32_e32 v89, v89, v103
	ds_write_b16 v191, v90 offset:22960
	v_mul_f32_e32 v90, v131, v102
	v_cvt_pk_bf16_f32 v102, v89, s0
	v_mul_f32_e32 v103, 0x3fb8aa3b, v149
	ds_write_b16 v191, v102 offset:5824
	v_mul_f32_e32 v102, 0xbfb8aa3b, v132
	v_exp_f32_e32 v103, v103
	v_exp_f32_e32 v102, v102
	v_mul_f32_e32 v89, v119, v89
	v_cvt_pk_bf16_f32 v89, v89, s0
	v_mul_f32_e32 v88, v88, v103
	ds_write_b16 v191, v89 offset:23232
	v_mul_f32_e32 v89, v133, v102
	v_cvt_pk_bf16_f32 v102, v88, s0
	v_mul_f32_e32 v103, 0x3fb8aa3b, v153
	ds_write_b16 v191, v102 offset:6096
	v_mul_f32_e32 v102, 0xbfb8aa3b, v149
	v_exp_f32_e32 v103, v103
	v_exp_f32_e32 v102, v102
	v_mul_f32_e32 v88, v119, v88
	v_cvt_pk_bf16_f32 v88, v88, s0
	v_mul_f32_e32 v87, v87, v103
	ds_write_b16 v191, v88 offset:23504
	v_mul_f32_e32 v88, v151, v102
	v_cvt_pk_bf16_f32 v102, v87, s0
	v_mul_f32_e32 v103, 0x3fb8aa3b, v155
	ds_write_b16 v191, v102 offset:6368
	v_mul_f32_e32 v102, 0xbfb8aa3b, v153
	v_exp_f32_e32 v103, v103
	v_exp_f32_e32 v102, v102
	v_mul_f32_e32 v87, v119, v87
	v_cvt_pk_bf16_f32 v87, v87, s0
	v_mul_f32_e32 v86, v86, v103
	ds_write_b16 v191, v87 offset:23776
	v_mul_f32_e32 v87, v158, v102
	v_cvt_pk_bf16_f32 v102, v86, s0
	ds_write_b16 v191, v102 offset:6640
	v_mul_f32_e32 v102, 0xbfb8aa3b, v155
	v_exp_f32_e32 v102, v102
	v_mul_f32_e32 v86, v119, v86
	v_cvt_pk_bf16_f32 v86, v86, s0
	ds_write_b16 v191, v86 offset:24048
	v_mul_f32_e32 v86, v159, v102
	s_and_saveexec_b64 s[0:1], s[2:3]
	s_cbranch_execnz .LBB0_1397
	s_or_b64 exec, exec, s[0:1]
	s_and_saveexec_b64 s[0:1], s[4:5]
	s_cbranch_execnz .LBB0_1398
